# hb-writing epilogues: row-sum cross-lane steps via v_permlane16/32_swap instead of ds_bpermute round trips
# baseline (speedup 1.0000x reference)
; #define EP_LOAD(q) do { _Pragma("unroll") for (int bj = 0; bj < 2; ++bj) { const unsigned o = ER_OFF(q, bj); t[(q) & 1][bj] = *(const u32x4*)(base + o); pw[(q) & 1][bj] = *(const u32x4*)(pp + o); } } while (0)
; __device__ __forceinline__ void load_rstd(float (&rsv)[2][4], const ssq_t* ssq, int row0) {
;     ssq_t t[2][4];
; #pragma unroll
;     for (int ai = 0; ai < 2; ++ai)
; #pragma unroll
;         for (int m = 0; m < 4; ++m) t[ai][m] = ssq[row0 + ai * HALF + m * 16];
; #pragma unroll
;     for (int ai = 0; ai < 2; ++ai)
; #pragma unroll
;         for (int m = 0; m < 4; ++m) rsv[ai][m] = __builtin_amdgcn_rsqf((float)t[ai][m] * (SSQ_INV / 1024.0f) + 1e-6f);
;     __device__ __forceinline__ void operator()(f32x4 (&acc)[2][2][4][2], const Unit& u, int wr, int wc, int fr, int fq) const {
;         const int row0 = u.pm * BM + wr * 64 + fr, col0 = u.pn * BM + wc * 32 + 8 * fq; const unsigned off0 = (unsigned)row0 * 1024u + (unsigned)col0;
;         float rsv[2][4]; load_rstd(rsv, ssq, row0);
;         u32x4 t[2][2], pw[2][2];
;     ...
;         bf16_t* hb = pp;
;         EP_LOAD(0); EP_LOAD(1); EP_ADD(0); EP_ADD(1);
.LBB0_238:
	v_mov_b32_e32 v128, v170
	s_lshl_b32 s13, s69, 8
	v_readfirstlane_b32 s12, v128
	s_ashr_i32 s46, s12, 2
	s_andn2_b32 s46, s46, 63
	s_lshr_b32 s12, s12, 1
	s_add_i32 s46, s46, s13
	s_lshl_b32 s13, s68, 8
	s_and_b32 s12, s12, 0x60
	v_bfe_u32 v199, v128, 4, 2
	v_and_or_b32 v192, v128, 15, s46
	s_or_b32 s12, s12, s13
	v_lshl_or_b32 v128, v199, 3, s12
	v_ashrrev_i32_e32 v193, 31, v192
	v_lshl_add_u32 v190, v192, 10, v128
	v_lshl_add_u64 v[128:129], v[192:193], 3, s[26:27]
	global_load_dwordx2 v[130:131], v[128:129], off
	global_load_dwordx2 v[212:213], v[128:129], off offset:128
	global_load_dwordx2 v[202:203], v[128:129], off offset:256
	global_load_dwordx2 v[196:197], v[128:129], off offset:384
	global_load_dwordx2 v[194:195], v[128:129], off offset:1024
	global_load_dwordx2 v[188:189], v[128:129], off offset:1152
	global_load_dwordx2 v[186:187], v[128:129], off offset:1280
	global_load_dwordx2 v[166:167], v[128:129], off offset:1408
	v_mov_b32_e32 v191, v169
	v_add_u32_e32 v168, 0x4000, v190
	v_cmp_eq_u32_e32 vcc, 0, v199
	v_cmp_lt_i32_e64 s[12:13], v233, v228
	v_lshl_add_u64 v[192:193], v[192:193], 3, s[40:41]
	v_lshlrev_b64 v[136:137], 1, v[190:191]
	v_lshl_add_u64 v[138:139], s[70:71], 0, v[136:137]
	global_load_dwordx4 v[152:155], v[138:139], off
	v_lshl_add_u64 v[214:215], s[20:21], 0, v[136:137]
	global_load_dwordx4 v[156:159], v[214:215], off
	global_load_dwordx4 v[144:147], v[138:139], off offset:256
	global_load_dwordx4 v[148:151], v[214:215], off offset:256
	s_waitcnt vmcnt(4)
	v_ffbh_u32_e32 v128, v131
	v_min_u32_e32 v132, 32, v128
	v_lshlrev_b64 v[128:129], v132, v[130:131]
	v_min_u32_e32 v128, 1, v128
	v_or_b32_e32 v128, v129, v128
	v_cvt_f32_u32_e32 v128, v128
	v_sub_u32_e32 v129, 32, v132
	v_ldexp_f32 v128, v128, v129
	v_fmamk_f32 v128, v128, 0x30800000, v223
	v_rsq_f32_e32 v198, v128
	s_nop 1
	v_pk_mul_f32 v[200:201], v[120:121], v[198:199] op_sel_hi:[1,0]
	v_pk_mul_f32 v[120:121], v[126:127], v[198:199] op_sel_hi:[1,0]
	v_mul_f32_e32 v127, 0xbfb8aa3b, v200
	v_exp_f32_e32 v127, v127
	v_pk_mul_f32 v[122:123], v[122:123], v[198:199] op_sel_hi:[1,0]
	v_pk_mul_f32 v[124:125], v[124:125], v[198:199] op_sel_hi:[1,0]
	v_mul_f32_e32 v122, 0xbfb8aa3b, v122
	v_add_f32_e32 v127, 1.0, v127
	v_rcp_f32_e32 v127, v127
	v_exp_f32_e32 v122, v122
	v_mul_f32_e32 v123, 0xbfb8aa3b, v123
	v_exp_f32_e32 v123, v123
	v_mul_f32_e32 v120, 0xbfb8aa3b, v120
	v_add_f32_e32 v122, 1.0, v122
	v_rcp_f32_e32 v122, v122
	v_add_f32_e32 v123, 1.0, v123
	v_rcp_f32_e32 v123, v123
	v_exp_f32_e32 v120, v120
	v_mul_f32_e32 v121, 0xbfb8aa3b, v121
	v_pk_mul_f32 v[116:117], v[116:117], v[198:199] op_sel_hi:[1,0]
	v_exp_f32_e32 v121, v121
	v_mul_f32_e32 v116, 0xbfb8aa3b, v116
	v_exp_f32_e32 v116, v116
	v_mul_f32_e32 v117, 0xbfb8aa3b, v117
	v_exp_f32_e32 v117, v117
	v_add_f32_e32 v120, 1.0, v120
	v_rcp_f32_e32 v120, v120
	v_add_f32_e32 v121, 1.0, v121
	v_rcp_f32_e32 v121, v121
	v_add_f32_e32 v116, 1.0, v116
	v_rcp_f32_e32 v116, v116
	v_add_f32_e32 v117, 1.0, v117
	v_rcp_f32_e32 v117, v117
	v_pk_mul_f32 v[118:119], v[118:119], v[198:199] op_sel_hi:[1,0]
	v_pk_mul_f32 v[112:113], v[112:113], v[198:199] op_sel_hi:[1,0]
	v_pk_mul_f32 v[114:115], v[114:115], v[198:199] op_sel_hi:[1,0]
	v_mul_f32_e32 v112, 0xbfb8aa3b, v112
	v_exp_f32_e32 v112, v112
	v_mul_f32_e32 v113, 0xbfb8aa3b, v113
	v_exp_f32_e32 v113, v113
	v_lshlrev_b64 v[128:129], 1, v[168:169]
	v_add_f32_e32 v112, 1.0, v112
	v_rcp_f32_e32 v112, v112
	v_add_f32_e32 v113, 1.0, v113
	v_rcp_f32_e32 v113, v113
	v_add_u32_e32 v168, 0x4080, v190
	v_lshlrev_b64 v[132:133], 1, v[168:169]
	v_add_u32_e32 v168, 0x8000, v190
	v_lshl_add_u64 v[130:131], s[70:71], 0, v[128:129]
	global_load_dwordx4 v[136:139], v[130:131], off
	v_lshl_add_u64 v[210:211], s[20:21], 0, v[128:129]
	v_lshl_add_u64 v[128:129], s[70:71], 0, v[132:133]
	v_lshl_add_u64 v[206:207], s[20:21], 0, v[132:133]
	global_load_dwordx4 v[140:143], v[210:211], off
	global_load_dwordx4 v[132:135], v[206:207], off
	s_waitcnt vmcnt(5)
	v_lshlrev_b32_e32 v126, 16, v156
	v_lshlrev_b32_e32 v191, 16, v152
	v_fmac_f32_e32 v191, v127, v126
	v_mul_f32_e32 v127, 0xbfb8aa3b, v201
	v_exp_f32_e32 v127, v127
	v_and_b32_e32 v220, 0xffff0000, v152
	v_and_b32_e32 v126, 0xffff0000, v156
	v_lshlrev_b32_e32 v221, 16, v153
	v_add_f32_e32 v127, 1.0, v127
	v_rcp_f32_e32 v127, v127
	v_and_b32_e32 v239, 0xffff0000, v153
	v_lshlrev_b32_e32 v240, 16, v154
	v_and_b32_e32 v241, 0xffff0000, v154
	v_fmac_f32_e32 v220, v127, v126
	v_lshlrev_b32_e32 v126, 16, v157
	v_fmac_f32_e32 v221, v122, v126
	v_and_b32_e32 v122, 0xffff0000, v157
	v_fmac_f32_e32 v239, v123, v122
	v_mul_f32_e32 v123, 0xbfb8aa3b, v124
	v_exp_f32_e32 v123, v123
	v_lshlrev_b32_e32 v122, 16, v158
	v_lshlrev_b32_e32 v242, 16, v155
	v_and_b32_e32 v243, 0xffff0000, v155
	v_add_f32_e32 v123, 1.0, v123
	v_rcp_f32_e32 v123, v123
	s_waitcnt vmcnt(4)
	v_lshlrev_b32_e32 v226, 16, v144
	v_and_b32_e32 v227, 0xffff0000, v144
	v_lshlrev_b32_e32 v237, 16, v145
	v_fmac_f32_e32 v240, v123, v122
	v_mul_f32_e32 v123, 0xbfb8aa3b, v125
	v_exp_f32_e32 v123, v123
	v_and_b32_e32 v122, 0xffff0000, v158
	v_and_b32_e32 v248, 0xffff0000, v145
	v_lshlrev_b32_e32 v249, 16, v146
	v_add_f32_e32 v123, 1.0, v123
	v_rcp_f32_e32 v123, v123
	v_and_b32_e32 v250, 0xffff0000, v146
	v_lshlrev_b32_e32 v251, 16, v147
	v_and_b32_e32 v252, 0xffff0000, v147
	v_fmac_f32_e32 v241, v123, v122
	v_lshlrev_b32_e32 v122, 16, v159
	v_fmac_f32_e32 v242, v120, v122
	v_and_b32_e32 v120, 0xffff0000, v159
	v_fmac_f32_e32 v243, v121, v120
	s_waitcnt vmcnt(3)
; #define EP_LOAD(q) do { _Pragma("unroll") for (int bj = 0; bj < 2; ++bj) { const unsigned o = ER_OFF(q, bj); t[(q) & 1][bj] = *(const u32x4*)(base + o); pw[(q) & 1][bj] = *(const u32x4*)(pp + o); } } while (0)
;     __device__ __forceinline__ void operator()(f32x4 (&acc)[2][2][4][2], const Unit& u, int wr, int wc, int fr, int fq) const {
;     ...
;         bf16_t* hb = pp;
;         EP_LOAD(0); EP_LOAD(1); EP_ADD(0); EP_ADD(1);
; #pragma unroll
;         for (int q = 0; q < 8; q += 2) { if (q < 6) { EP_LOAD(q + 2); EP_LOAD(q + 3); } ER_STORE(q); ER_STORE(q + 1); if (q < 6) { EP_ADD(q + 2); EP_ADD(q + 3); } }
	v_lshlrev_b32_e32 v120, 16, v148
	v_fmac_f32_e32 v226, v116, v120
	v_and_b32_e32 v116, 0xffff0000, v148
	v_fmac_f32_e32 v227, v117, v116
	v_mul_f32_e32 v117, 0xbfb8aa3b, v118
	v_exp_f32_e32 v117, v117
	v_lshlrev_b32_e32 v116, 16, v149
	v_add_f32_e32 v117, 1.0, v117
	v_rcp_f32_e32 v117, v117
	s_nop 0
	v_fmac_f32_e32 v237, v117, v116
	v_mul_f32_e32 v117, 0xbfb8aa3b, v119
	v_exp_f32_e32 v117, v117
	v_and_b32_e32 v116, 0xffff0000, v149
	v_add_f32_e32 v117, 1.0, v117
	v_rcp_f32_e32 v117, v117
	s_nop 0
	v_fmac_f32_e32 v248, v117, v116
	v_lshlrev_b32_e32 v116, 16, v150
	v_fmac_f32_e32 v249, v112, v116
	v_and_b32_e32 v112, 0xffff0000, v150
	v_fmac_f32_e32 v250, v113, v112
	v_mul_f32_e32 v113, 0xbfb8aa3b, v114
	v_exp_f32_e32 v113, v113
	v_lshlrev_b32_e32 v112, 16, v151
	v_add_f32_e32 v113, 1.0, v113
	v_rcp_f32_e32 v113, v113
	s_nop 0
	v_fmac_f32_e32 v251, v113, v112
	v_mul_f32_e32 v113, 0xbfb8aa3b, v115
	v_exp_f32_e32 v113, v113
	v_and_b32_e32 v112, 0xffff0000, v151
	v_add_f32_e32 v113, 1.0, v113
	v_rcp_f32_e32 v113, v113
	s_nop 0
	v_fmac_f32_e32 v252, v113, v112
	v_lshlrev_b64 v[112:113], 1, v[168:169]
	v_add_u32_e32 v168, 0x8080, v190
	v_lshl_add_u64 v[114:115], s[70:71], 0, v[112:113]
	v_lshl_add_u64 v[208:209], s[20:21], 0, v[112:113]
	v_lshlrev_b64 v[112:113], 1, v[168:169]
	v_add_u32_e32 v168, 0xc000, v190
	global_load_dwordx4 v[152:155], v[114:115], off
	v_lshl_add_u64 v[114:115], s[70:71], 0, v[112:113]
	v_lshl_add_u64 v[204:205], s[20:21], 0, v[112:113]
	v_lshlrev_b64 v[112:113], 1, v[168:169]
	v_add_u32_e32 v168, 0xc080, v190
	v_lshl_add_u64 v[200:201], s[20:21], 0, v[112:113]
	v_lshlrev_b64 v[116:117], 1, v[168:169]
	global_load_dwordx4 v[144:147], v[114:115], off
	global_load_dwordx4 v[124:127], v[200:201], off
	v_lshl_add_u64 v[114:115], s[70:71], 0, v[112:113]
	v_lshl_add_u64 v[112:113], s[70:71], 0, v[116:117]
	v_lshl_add_u64 v[198:199], s[20:21], 0, v[116:117]
	global_load_dwordx4 v[128:131], v[128:129], off
	s_nop 0
	global_load_dwordx4 v[156:159], v[208:209], off
	global_load_dwordx4 v[148:151], v[204:205], off
	global_load_dwordx4 v[120:123], v[114:115], off
	global_load_dwordx4 v[116:119], v[198:199], off
	s_nop 0
	global_load_dwordx4 v[112:115], v[112:113], off
	v_cvt_pk_bf16_f32 v244, v191, v220
	v_cvt_pk_bf16_f32 v245, v221, v239
	v_cvt_pk_bf16_f32 v246, v240, v241
	v_cvt_pk_bf16_f32 v247, v242, v243
	global_store_dwordx4 v[214:215], v[244:247], off
	v_and_b32_e32 v191, 0xffff0000, v244
	v_lshlrev_b32_e32 v168, 16, v244
	v_mul_f32_e32 v191, v191, v191
	v_and_b32_e32 v220, 0xffff0000, v245
	v_fmac_f32_e32 v191, v168, v168
	v_lshlrev_b32_e32 v168, 16, v245
	v_mul_f32_e32 v220, v220, v220
	v_fmac_f32_e32 v220, v168, v168
	v_add_f32_e32 v168, v191, v220
	v_and_b32_e32 v220, 0xffff0000, v246
	v_lshlrev_b32_e32 v191, 16, v246
	v_mul_f32_e32 v220, v220, v220
	v_fmac_f32_e32 v220, v191, v191
	v_add_f32_e32 v168, v168, v220
	v_and_b32_e32 v220, 0xffff0000, v247
	v_lshlrev_b32_e32 v191, 16, v247
	v_mul_f32_e32 v220, v220, v220
	v_cvt_pk_bf16_f32 v240, v226, v227
	v_cvt_pk_bf16_f32 v241, v237, v248
	v_cvt_pk_bf16_f32 v242, v249, v250
	v_cvt_pk_bf16_f32 v243, v251, v252
	global_store_dwordx4 v[214:215], v[240:243], off offset:256
	v_and_b32_e32 v214, 0xffff0000, v240
	v_fmac_f32_e32 v220, v191, v191
	v_lshlrev_b32_e32 v191, 16, v240
	v_mul_f32_e32 v214, v214, v214
	v_add_f32_e32 v168, v168, v220
	v_fmac_f32_e32 v214, v191, v191
	v_add_f32_e32 v168, v168, v214
	v_and_b32_e32 v214, 0xffff0000, v241
	v_lshlrev_b32_e32 v191, 16, v241
	v_mul_f32_e32 v214, v214, v214
	v_fmac_f32_e32 v214, v191, v191
	v_add_f32_e32 v168, v168, v214
	v_and_b32_e32 v214, 0xffff0000, v242
	v_lshlrev_b32_e32 v191, 16, v242
	v_mul_f32_e32 v214, v214, v214
	v_fmac_f32_e32 v214, v191, v191
	v_add_f32_e32 v168, v168, v214
	v_and_b32_e32 v214, 0xffff0000, v243
	v_lshlrev_b32_e32 v191, 16, v243
	v_mul_f32_e32 v214, v214, v214
	v_fmac_f32_e32 v214, v191, v191
	v_cndmask_b32_e64 v191, v225, v233, s[12:13]
	v_add_f32_e32 v168, v168, v214
	v_lshlrev_b32_e32 v191, 2, v191
	v_mov_b32_e32 v214, v168
	s_nop 1
	v_permlane16_swap_b32_e32 v214, v168
	s_nop 1
	v_cmp_lt_i32_e64 s[12:13], v234, v228
	s_waitcnt lgkmcnt(0)
	v_add_f32_e32 v168, v168, v214
	v_cndmask_b32_e64 v214, v225, v234, s[12:13]
	v_lshlrev_b32_e32 v214, 2, v214
	v_mov_b32_e32 v215, v168
	s_nop 1
	v_permlane32_swap_b32_e32 v215, v168
	s_nop 1
	s_and_saveexec_b64 s[12:13], vcc
	s_cbranch_execz .LBB0_240
	s_waitcnt lgkmcnt(0)
	v_add_f32_e32 v168, v168, v215
	v_mul_f32_e32 v168, 0x49800000, v168
	v_trunc_f32_e32 v168, v168
	v_mul_f32_e32 v215, 0x2f800000, v168
	v_floor_f32_e32 v215, v215
	v_fmac_f32_e32 v168, 0xcf800000, v215
	v_cvt_u32_f32_e32 v220, v168
	v_cvt_u32_f32_e32 v221, v215
	global_atomic_add_x2 v[192:193], v[220:221], off
; #define EP_LOAD(q) do { _Pragma("unroll") for (int bj = 0; bj < 2; ++bj) { const unsigned o = ER_OFF(q, bj); t[(q) & 1][bj] = *(const u32x4*)(base + o); pw[(q) & 1][bj] = *(const u32x4*)(pp + o); } } while (0)
;     __device__ __forceinline__ void operator()(f32x4 (&acc)[2][2][4][2], const Unit& u, int wr, int wc, int fr, int fq) const {
;     ...
;         bf16_t* hb = pp;
;         EP_LOAD(0); EP_LOAD(1); EP_ADD(0); EP_ADD(1);
; #pragma unroll
;         for (int q = 0; q < 8; q += 2) { if (q < 6) { EP_LOAD(q + 2); EP_LOAD(q + 3); } ER_STORE(q); ER_STORE(q + 1); if (q < 6) { EP_ADD(q + 2); EP_ADD(q + 3); } }
.LBB0_240:
	s_or_b64 exec, exec, s[12:13]
	v_ffbh_u32_e32 v168, v213
	v_min_u32_e32 v168, 32, v168
	v_lshlrev_b64 v[212:213], v168, v[212:213]
	v_min_u32_e32 v212, 1, v212
	v_or_b32_e32 v212, v213, v212
	v_cvt_f32_u32_e32 v212, v212
	v_sub_u32_e32 v168, 32, v168
	s_waitcnt vmcnt(12)
	v_lshlrev_b32_e32 v213, 16, v140
	v_and_b32_e32 v140, 0xffff0000, v140
	v_ldexp_f32 v168, v212, v168
	v_fmamk_f32 v168, v168, 0x30800000, v223
	v_rsq_f32_e32 v168, v168
	v_lshlrev_b32_e32 v212, 16, v136
	v_and_b32_e32 v136, 0xffff0000, v136
	v_pk_mul_f32 v[108:109], v[108:109], v[168:169] op_sel_hi:[1,0]
	s_nop 0
	v_mul_f32_e32 v108, 0xbfb8aa3b, v108
	v_mul_f32_e32 v109, 0xbfb8aa3b, v109
	s_waitcnt lgkmcnt(0)
	v_exp_f32_e32 v215, v108
	v_exp_f32_e32 v220, v109
	v_pk_mul_f32 v[108:109], v[110:111], v[168:169] op_sel_hi:[1,0]
	v_pk_mul_f32 v[104:105], v[104:105], v[168:169] op_sel_hi:[1,0]
	v_mul_f32_e32 v108, 0xbfb8aa3b, v108
	v_exp_f32_e32 v108, v108
	v_mul_f32_e32 v109, 0xbfb8aa3b, v109
	v_exp_f32_e32 v109, v109
	v_mul_f32_e32 v104, 0xbfb8aa3b, v104
	v_exp_f32_e32 v104, v104
	v_mul_f32_e32 v105, 0xbfb8aa3b, v105
	v_add_f32_e32 v110, 1.0, v215
	v_add_f32_e32 v111, 1.0, v220
	v_exp_f32_e32 v105, v105
	v_rcp_f32_e32 v110, v110
	v_rcp_f32_e32 v111, v111
	v_add_f32_e32 v108, 1.0, v108
	v_rcp_f32_e32 v108, v108
	v_add_f32_e32 v109, 1.0, v109
	v_rcp_f32_e32 v109, v109
	v_add_f32_e32 v104, 1.0, v104
	v_rcp_f32_e32 v104, v104
	v_add_f32_e32 v105, 1.0, v105
	v_fmac_f32_e32 v212, v110, v213
	v_fmac_f32_e32 v136, v111, v140
	v_lshlrev_b32_e32 v110, 16, v137
	v_lshlrev_b32_e32 v111, 16, v141
	v_rcp_f32_e32 v105, v105
	v_fmac_f32_e32 v110, v108, v111
	v_and_b32_e32 v108, 0xffff0000, v137
	v_and_b32_e32 v111, 0xffff0000, v141
	v_fmac_f32_e32 v108, v109, v111
	v_lshlrev_b32_e32 v109, 16, v138
	v_lshlrev_b32_e32 v111, 16, v142
	v_pk_mul_f32 v[106:107], v[106:107], v[168:169] op_sel_hi:[1,0]
	v_fmac_f32_e32 v109, v104, v111
	v_and_b32_e32 v104, 0xffff0000, v138
	v_and_b32_e32 v111, 0xffff0000, v142
	v_fmac_f32_e32 v104, v105, v111
	v_mul_f32_e32 v105, 0xbfb8aa3b, v106
	v_exp_f32_e32 v105, v105
	v_mul_f32_e32 v107, 0xbfb8aa3b, v107
	v_pk_mul_f32 v[100:101], v[100:101], v[168:169] op_sel_hi:[1,0]
	v_exp_f32_e32 v107, v107
	v_mul_f32_e32 v100, 0xbfb8aa3b, v100
	v_exp_f32_e32 v100, v100
	v_mul_f32_e32 v101, 0xbfb8aa3b, v101
	v_exp_f32_e32 v101, v101
	v_add_f32_e32 v105, 1.0, v105
	v_rcp_f32_e32 v105, v105
	v_add_f32_e32 v107, 1.0, v107
	v_rcp_f32_e32 v107, v107
	v_add_f32_e32 v100, 1.0, v100
	v_rcp_f32_e32 v100, v100
	v_add_f32_e32 v101, 1.0, v101
	v_lshlrev_b32_e32 v106, 16, v139
	v_lshlrev_b32_e32 v111, 16, v143
	v_rcp_f32_e32 v101, v101
	v_fmac_f32_e32 v106, v105, v111
	v_and_b32_e32 v105, 0xffff0000, v139
	v_and_b32_e32 v111, 0xffff0000, v143
	v_fmac_f32_e32 v105, v107, v111
	s_waitcnt vmcnt(7)
	v_lshlrev_b32_e32 v107, 16, v128
	v_lshlrev_b32_e32 v111, 16, v132
	v_pk_mul_f32 v[102:103], v[102:103], v[168:169] op_sel_hi:[1,0]
	v_fmac_f32_e32 v107, v100, v111
	v_and_b32_e32 v100, 0xffff0000, v128
	v_and_b32_e32 v111, 0xffff0000, v132
	v_fmac_f32_e32 v100, v101, v111
	v_mul_f32_e32 v101, 0xbfb8aa3b, v102
	v_pk_mul_f32 v[96:97], v[96:97], v[168:169] op_sel_hi:[1,0]
	v_exp_f32_e32 v101, v101
	v_mul_f32_e32 v103, 0xbfb8aa3b, v103
	v_exp_f32_e32 v103, v103
	v_mul_f32_e32 v96, 0xbfb8aa3b, v96
	v_exp_f32_e32 v96, v96
	v_mul_f32_e32 v97, 0xbfb8aa3b, v97
	v_exp_f32_e32 v97, v97
	v_add_f32_e32 v101, 1.0, v101
	v_rcp_f32_e32 v101, v101
	v_add_f32_e32 v103, 1.0, v103
	v_rcp_f32_e32 v103, v103
	v_add_f32_e32 v96, 1.0, v96
	v_rcp_f32_e32 v96, v96
	v_add_f32_e32 v97, 1.0, v97
	v_lshlrev_b32_e32 v102, 16, v129
	v_lshlrev_b32_e32 v111, 16, v133
	v_rcp_f32_e32 v97, v97
	v_fmac_f32_e32 v102, v101, v111
	v_and_b32_e32 v101, 0xffff0000, v129
	v_and_b32_e32 v111, 0xffff0000, v133
	v_fmac_f32_e32 v101, v103, v111
	v_lshlrev_b32_e32 v103, 16, v130
	v_lshlrev_b32_e32 v111, 16, v134
	v_pk_mul_f32 v[98:99], v[98:99], v[168:169] op_sel_hi:[1,0]
	v_fmac_f32_e32 v103, v96, v111
	v_and_b32_e32 v111, 0xffff0000, v130
	v_and_b32_e32 v96, 0xffff0000, v134
	v_fmac_f32_e32 v111, v97, v96
	v_mul_f32_e32 v96, 0xbfb8aa3b, v98
	v_exp_f32_e32 v96, v96
	v_mul_f32_e32 v97, 0xbfb8aa3b, v99
	v_exp_f32_e32 v97, v97
	v_lshlrev_b32_e32 v128, 16, v131
	v_add_f32_e32 v96, 1.0, v96
	v_rcp_f32_e32 v96, v96
	v_add_f32_e32 v97, 1.0, v97
	v_rcp_f32_e32 v97, v97
	v_lshlrev_b32_e32 v98, 16, v135
	v_fmac_f32_e32 v128, v96, v98
	v_and_b32_e32 v129, 0xffff0000, v131
	v_and_b32_e32 v96, 0xffff0000, v135
	v_fmac_f32_e32 v129, v97, v96
	v_cvt_pk_bf16_f32 v96, v212, v136
	v_cvt_pk_bf16_f32 v97, v110, v108
	v_cvt_pk_bf16_f32 v98, v109, v104
	v_cvt_pk_bf16_f32 v99, v106, v105
	global_store_dwordx4 v[210:211], v[96:99], off
	v_lshlrev_b32_e32 v104, 16, v96
	s_nop 0
	v_and_b32_e32 v96, 0xffff0000, v96
	v_mul_f32_e32 v96, v96, v96
	v_fmac_f32_e32 v96, v104, v104
	v_lshlrev_b32_e32 v104, 16, v97
	v_and_b32_e32 v97, 0xffff0000, v97
	v_mul_f32_e32 v97, v97, v97
	v_fmac_f32_e32 v97, v104, v104
	v_add_f32_e32 v96, v96, v97
	v_lshlrev_b32_e32 v97, 16, v98
	v_and_b32_e32 v98, 0xffff0000, v98
	v_mul_f32_e32 v98, v98, v98
	v_fmac_f32_e32 v98, v97, v97
	v_add_f32_e32 v96, v96, v98
	v_and_b32_e32 v98, 0xffff0000, v99
	v_lshlrev_b32_e32 v97, 16, v99
	v_mul_f32_e32 v98, v98, v98
	v_fmac_f32_e32 v98, v97, v97
	v_add_f32_e32 v96, v96, v98
	v_cvt_pk_bf16_f32 v98, v107, v100
	v_cvt_pk_bf16_f32 v99, v102, v101
	v_cvt_pk_bf16_f32 v100, v103, v111
	v_cvt_pk_bf16_f32 v101, v128, v129
	global_store_dwordx4 v[206:207], v[98:101], off
	v_and_b32_e32 v102, 0xffff0000, v98
	v_lshlrev_b32_e32 v97, 16, v98
	v_mul_f32_e32 v102, v102, v102
	v_fmac_f32_e32 v102, v97, v97
	v_add_f32_e32 v96, v96, v102
	v_and_b32_e32 v102, 0xffff0000, v99
	v_lshlrev_b32_e32 v97, 16, v99
	v_mul_f32_e32 v102, v102, v102
	v_fmac_f32_e32 v102, v97, v97
	v_add_f32_e32 v96, v96, v102
	v_and_b32_e32 v102, 0xffff0000, v100
	v_lshlrev_b32_e32 v97, 16, v100
	v_mul_f32_e32 v102, v102, v102
	v_fmac_f32_e32 v102, v97, v97
	v_add_f32_e32 v96, v96, v102
	v_and_b32_e32 v102, 0xffff0000, v101
	v_lshlrev_b32_e32 v97, 16, v101
	v_mul_f32_e32 v102, v102, v102
	v_fmac_f32_e32 v102, v97, v97
	v_add_f32_e32 v96, v96, v102
	v_mov_b32_e32 v97, v96
	s_nop 1
	v_permlane16_swap_b32_e32 v97, v96
	s_nop 1
	s_waitcnt lgkmcnt(0)
	v_add_f32_e32 v96, v96, v97
	v_mov_b32_e32 v97, v96
	s_nop 1
	v_permlane32_swap_b32_e32 v97, v96
	s_nop 1
	s_and_saveexec_b64 s[12:13], vcc
	s_cbranch_execz .LBB0_242
	s_waitcnt lgkmcnt(0)
	v_add_f32_e32 v96, v96, v97
	v_mul_f32_e32 v96, 0x49800000, v96
	v_trunc_f32_e32 v96, v96
	v_mul_f32_e32 v97, 0x2f800000, v96
	v_floor_f32_e32 v97, v97
	v_fmac_f32_e32 v96, 0xcf800000, v97
	v_cvt_u32_f32_e32 v96, v96
	v_cvt_u32_f32_e32 v97, v97
	global_atomic_add_x2 v[192:193], v[96:97], off offset:128
; #define EP_LOAD(q) do { _Pragma("unroll") for (int bj = 0; bj < 2; ++bj) { const unsigned o = ER_OFF(q, bj); t[(q) & 1][bj] = *(const u32x4*)(base + o); pw[(q) & 1][bj] = *(const u32x4*)(pp + o); } } while (0)
;     __device__ __forceinline__ void operator()(f32x4 (&acc)[2][2][4][2], const Unit& u, int wr, int wc, int fr, int fq) const {
;     ...
;         bf16_t* hb = pp;
;         EP_LOAD(0); EP_LOAD(1); EP_ADD(0); EP_ADD(1);
; #pragma unroll
;         for (int q = 0; q < 8; q += 2) { if (q < 6) { EP_LOAD(q + 2); EP_LOAD(q + 3); } ER_STORE(q); ER_STORE(q + 1); if (q < 6) { EP_ADD(q + 2); EP_ADD(q + 3); } }
.LBB0_242:
	s_or_b64 exec, exec, s[12:13]
	v_ffbh_u32_e32 v96, v203
	v_min_u32_e32 v98, 32, v96
	s_waitcnt lgkmcnt(0)
	v_lshlrev_b64 v[96:97], v98, v[202:203]
	v_min_u32_e32 v96, 1, v96
	v_or_b32_e32 v96, v97, v96
	v_cvt_f32_u32_e32 v96, v96
	v_sub_u32_e32 v97, 32, v98
	v_lshlrev_b32_e32 v136, 16, v152
	v_and_b32_e32 v137, 0xffff0000, v152
	v_ldexp_f32 v96, v96, v97
	v_fmamk_f32 v96, v96, 0x30800000, v223
	v_rsq_f32_e32 v96, v96
	v_lshlrev_b32_e32 v138, 16, v153
	v_and_b32_e32 v139, 0xffff0000, v153
	v_lshlrev_b32_e32 v140, 16, v154
	v_pk_mul_f32 v[92:93], v[92:93], v[96:97] op_sel_hi:[1,0]
	v_pk_mul_f32 v[94:95], v[94:95], v[96:97] op_sel_hi:[1,0]
	v_mul_f32_e32 v92, 0xbfb8aa3b, v92
	v_exp_f32_e32 v92, v92
	v_mul_f32_e32 v93, 0xbfb8aa3b, v93
	v_exp_f32_e32 v93, v93
	v_pk_mul_f32 v[90:91], v[90:91], v[96:97] op_sel_hi:[1,0]
	v_add_f32_e32 v92, 1.0, v92
	v_rcp_f32_e32 v92, v92
	v_add_f32_e32 v93, 1.0, v93
	v_rcp_f32_e32 v93, v93
	v_pk_mul_f32 v[88:89], v[88:89], v[96:97] op_sel_hi:[1,0]
	s_waitcnt vmcnt(8)
	v_lshlrev_b32_e32 v97, 16, v156
	v_fmac_f32_e32 v136, v92, v97
	v_and_b32_e32 v92, 0xffff0000, v156
	v_fmac_f32_e32 v137, v93, v92
	v_mul_f32_e32 v93, 0xbfb8aa3b, v94
	v_exp_f32_e32 v93, v93
	v_lshlrev_b32_e32 v92, 16, v157
	v_mul_f32_e32 v88, 0xbfb8aa3b, v88
	v_exp_f32_e32 v88, v88
	v_add_f32_e32 v93, 1.0, v93
	v_rcp_f32_e32 v93, v93
	v_mul_f32_e32 v89, 0xbfb8aa3b, v89
	v_exp_f32_e32 v89, v89
	v_add_f32_e32 v88, 1.0, v88
	v_fmac_f32_e32 v138, v93, v92
	v_mul_f32_e32 v93, 0xbfb8aa3b, v95
	v_exp_f32_e32 v93, v93
	v_rcp_f32_e32 v88, v88
	v_add_f32_e32 v89, 1.0, v89
	v_rcp_f32_e32 v89, v89
	v_add_f32_e32 v93, 1.0, v93
	v_rcp_f32_e32 v93, v93
	v_and_b32_e32 v92, 0xffff0000, v157
	v_and_b32_e32 v141, 0xffff0000, v154
	v_lshlrev_b32_e32 v142, 16, v155
	v_fmac_f32_e32 v139, v93, v92
	v_lshlrev_b32_e32 v92, 16, v158
	v_fmac_f32_e32 v140, v88, v92
	v_and_b32_e32 v88, 0xffff0000, v158
	v_fmac_f32_e32 v141, v89, v88
	v_mul_f32_e32 v89, 0xbfb8aa3b, v90
	v_exp_f32_e32 v89, v89
	v_lshlrev_b32_e32 v88, 16, v159
	v_pk_mul_f32 v[84:85], v[84:85], v[96:97] op_sel_hi:[1,0]
	v_and_b32_e32 v143, 0xffff0000, v155
	v_add_f32_e32 v89, 1.0, v89
	v_rcp_f32_e32 v89, v89
	v_mul_f32_e32 v84, 0xbfb8aa3b, v84
	v_exp_f32_e32 v84, v84
	v_mul_f32_e32 v85, 0xbfb8aa3b, v85
	v_fmac_f32_e32 v142, v89, v88
	v_mul_f32_e32 v89, 0xbfb8aa3b, v91
	v_exp_f32_e32 v89, v89
	v_exp_f32_e32 v85, v85
	v_add_f32_e32 v84, 1.0, v84
	v_rcp_f32_e32 v84, v84
	v_add_f32_e32 v89, 1.0, v89
	v_rcp_f32_e32 v89, v89
	v_add_f32_e32 v85, 1.0, v85
	v_rcp_f32_e32 v85, v85
	v_and_b32_e32 v88, 0xffff0000, v159
	v_fmac_f32_e32 v143, v89, v88
	v_lshlrev_b32_e32 v152, 16, v144
	s_waitcnt vmcnt(7)
	v_lshlrev_b32_e32 v88, 16, v148
	v_pk_mul_f32 v[86:87], v[86:87], v[96:97] op_sel_hi:[1,0]
	v_fmac_f32_e32 v152, v84, v88
	v_and_b32_e32 v144, 0xffff0000, v144
	v_and_b32_e32 v84, 0xffff0000, v148
	v_fmac_f32_e32 v144, v85, v84
	v_mul_f32_e32 v85, 0xbfb8aa3b, v86
	v_exp_f32_e32 v85, v85
	v_lshlrev_b32_e32 v148, 16, v145
	v_lshlrev_b32_e32 v84, 16, v149
	v_pk_mul_f32 v[80:81], v[80:81], v[96:97] op_sel_hi:[1,0]
	v_add_f32_e32 v85, 1.0, v85
	v_rcp_f32_e32 v85, v85
	v_mul_f32_e32 v80, 0xbfb8aa3b, v80
	v_exp_f32_e32 v80, v80
	v_mul_f32_e32 v81, 0xbfb8aa3b, v81
	v_fmac_f32_e32 v148, v85, v84
	v_mul_f32_e32 v85, 0xbfb8aa3b, v87
	v_exp_f32_e32 v85, v85
	v_exp_f32_e32 v81, v81
	v_add_f32_e32 v80, 1.0, v80
	v_rcp_f32_e32 v80, v80
	v_add_f32_e32 v85, 1.0, v85
	v_rcp_f32_e32 v85, v85
	v_add_f32_e32 v81, 1.0, v81
	v_rcp_f32_e32 v81, v81
	v_and_b32_e32 v145, 0xffff0000, v145
	v_and_b32_e32 v84, 0xffff0000, v149
	v_fmac_f32_e32 v145, v85, v84
	v_lshlrev_b32_e32 v149, 16, v146
	v_lshlrev_b32_e32 v84, 16, v150
	v_pk_mul_f32 v[82:83], v[82:83], v[96:97] op_sel_hi:[1,0]
	v_fmac_f32_e32 v149, v80, v84
	v_and_b32_e32 v146, 0xffff0000, v146
	v_and_b32_e32 v80, 0xffff0000, v150
	v_fmac_f32_e32 v146, v81, v80
	v_mul_f32_e32 v81, 0xbfb8aa3b, v82
	v_exp_f32_e32 v81, v81
	v_lshlrev_b32_e32 v150, 16, v147
	v_lshlrev_b32_e32 v80, 16, v151
	v_and_b32_e32 v147, 0xffff0000, v147
	v_add_f32_e32 v81, 1.0, v81
	v_rcp_f32_e32 v81, v81
	v_add_u32_e32 v168, 0x20000, v190
	v_fmac_f32_e32 v150, v81, v80
	v_mul_f32_e32 v81, 0xbfb8aa3b, v83
	v_exp_f32_e32 v81, v81
	v_and_b32_e32 v80, 0xffff0000, v151
	v_add_f32_e32 v81, 1.0, v81
	v_rcp_f32_e32 v81, v81
	s_nop 0
	v_fmac_f32_e32 v147, v81, v80
	v_lshlrev_b64 v[80:81], 1, v[168:169]
	v_add_u32_e32 v168, 0x20080, v190
	v_lshl_add_u64 v[82:83], s[70:71], 0, v[80:81]
	v_lshl_add_u64 v[134:135], s[20:21], 0, v[80:81]
	v_lshlrev_b64 v[80:81], 1, v[168:169]
	v_lshl_add_u64 v[132:133], s[20:21], 0, v[80:81]
	v_add_u32_e32 v168, 0x24000, v190
	global_load_dwordx4 v[104:107], v[82:83], off
	global_load_dwordx4 v[100:103], v[132:133], off
	v_lshl_add_u64 v[82:83], s[70:71], 0, v[80:81]
	v_lshlrev_b64 v[80:81], 1, v[168:169]
	v_add_u32_e32 v168, 0x24080, v190
	v_lshl_add_u64 v[130:131], s[20:21], 0, v[80:81]
	v_lshlrev_b64 v[84:85], 1, v[168:169]
	global_load_dwordx4 v[96:99], v[82:83], off
	global_load_dwordx4 v[92:95], v[130:131], off
	v_lshl_add_u64 v[82:83], s[70:71], 0, v[80:81]
	v_lshl_add_u64 v[80:81], s[70:71], 0, v[84:85]
	v_lshl_add_u64 v[128:129], s[20:21], 0, v[84:85]
	global_load_dwordx4 v[108:111], v[134:135], off
	global_load_dwordx4 v[88:91], v[82:83], off
	global_load_dwordx4 v[84:87], v[128:129], off
	s_nop 0
	global_load_dwordx4 v[80:83], v[80:81], off
	v_cvt_pk_bf16_f32 v136, v136, v137
	v_cvt_pk_bf16_f32 v137, v138, v139
	v_cvt_pk_bf16_f32 v138, v140, v141
	v_cvt_pk_bf16_f32 v139, v142, v143
	global_store_dwordx4 v[208:209], v[136:139], off
	v_lshlrev_b32_e32 v140, 16, v136
	s_nop 0
	v_and_b32_e32 v136, 0xffff0000, v136
	v_mul_f32_e32 v136, v136, v136
	v_fmac_f32_e32 v136, v140, v140
	v_lshlrev_b32_e32 v140, 16, v137
	v_and_b32_e32 v137, 0xffff0000, v137
	v_mul_f32_e32 v137, v137, v137
	v_fmac_f32_e32 v137, v140, v140
	v_add_f32_e32 v136, v136, v137
	v_lshlrev_b32_e32 v137, 16, v138
	v_and_b32_e32 v138, 0xffff0000, v138
	v_mul_f32_e32 v138, v138, v138
	v_fmac_f32_e32 v138, v137, v137
	v_add_f32_e32 v136, v136, v138
	v_and_b32_e32 v138, 0xffff0000, v139
	v_lshlrev_b32_e32 v137, 16, v139
	v_mul_f32_e32 v138, v138, v138
	v_fmac_f32_e32 v138, v137, v137
	v_add_f32_e32 v140, v136, v138
	v_cvt_pk_bf16_f32 v136, v152, v144
	v_cvt_pk_bf16_f32 v137, v148, v145
	v_cvt_pk_bf16_f32 v138, v149, v146
	v_cvt_pk_bf16_f32 v139, v150, v147
	global_store_dwordx4 v[204:205], v[136:139], off
	v_lshlrev_b32_e32 v141, 16, v136
	s_nop 0
	v_and_b32_e32 v136, 0xffff0000, v136
	v_mul_f32_e32 v136, v136, v136
	v_fmac_f32_e32 v136, v141, v141
	v_add_f32_e32 v136, v140, v136
	v_lshlrev_b32_e32 v140, 16, v137
	v_and_b32_e32 v137, 0xffff0000, v137
	v_mul_f32_e32 v137, v137, v137
	v_fmac_f32_e32 v137, v140, v140
	v_add_f32_e32 v136, v136, v137
	v_lshlrev_b32_e32 v137, 16, v138
	v_and_b32_e32 v138, 0xffff0000, v138
	v_mul_f32_e32 v138, v138, v138
	v_fmac_f32_e32 v138, v137, v137
	v_add_f32_e32 v136, v136, v138
	v_and_b32_e32 v138, 0xffff0000, v139
	v_lshlrev_b32_e32 v137, 16, v139
	v_mul_f32_e32 v138, v138, v138
	v_fmac_f32_e32 v138, v137, v137
	v_add_f32_e32 v136, v136, v138
	v_mov_b32_e32 v137, v136
	s_nop 1
	v_permlane16_swap_b32_e32 v137, v136
	s_nop 1
	s_waitcnt lgkmcnt(0)
	v_add_f32_e32 v136, v136, v137
	v_mov_b32_e32 v137, v136
	s_nop 1
	v_permlane32_swap_b32_e32 v137, v136
	s_nop 1
	s_and_saveexec_b64 s[12:13], vcc
	s_cbranch_execz .LBB0_244
	s_waitcnt lgkmcnt(0)
	v_add_f32_e32 v136, v136, v137
	v_mul_f32_e32 v136, 0x49800000, v136
	v_trunc_f32_e32 v136, v136
	v_mul_f32_e32 v137, 0x2f800000, v136
	v_floor_f32_e32 v137, v137
	v_fmac_f32_e32 v136, 0xcf800000, v137
	v_cvt_u32_f32_e32 v136, v136
	v_cvt_u32_f32_e32 v137, v137
	global_atomic_add_x2 v[192:193], v[136:137], off offset:256
.LBB0_244:
	s_or_b64 exec, exec, s[12:13]
	v_ffbh_u32_e32 v136, v197
	v_min_u32_e32 v138, 32, v136
	s_waitcnt lgkmcnt(0)
	v_lshlrev_b64 v[136:137], v138, v[196:197]
	v_min_u32_e32 v136, 1, v136
	v_or_b32_e32 v136, v137, v136
	v_cvt_f32_u32_e32 v136, v136
	v_sub_u32_e32 v137, 32, v138
	v_lshlrev_b32_e32 v138, 16, v124
	v_and_b32_e32 v124, 0xffff0000, v124
	v_ldexp_f32 v136, v136, v137
	v_fmamk_f32 v136, v136, 0x30800000, v223
	v_rsq_f32_e32 v136, v136
	s_waitcnt vmcnt(16)
	v_lshlrev_b32_e32 v137, 16, v120
	v_and_b32_e32 v120, 0xffff0000, v120
	v_pk_mul_f32 v[76:77], v[76:77], v[136:137] op_sel_hi:[1,0]
	s_nop 0
	v_mul_f32_e32 v76, 0xbfb8aa3b, v76
	v_mul_f32_e32 v77, 0xbfb8aa3b, v77
	v_exp_f32_e32 v139, v76
	v_exp_f32_e32 v140, v77
	v_pk_mul_f32 v[76:77], v[78:79], v[136:137] op_sel_hi:[1,0]
	v_pk_mul_f32 v[72:73], v[72:73], v[136:137] op_sel_hi:[1,0]
	v_mul_f32_e32 v76, 0xbfb8aa3b, v76
	v_exp_f32_e32 v76, v76
	v_mul_f32_e32 v77, 0xbfb8aa3b, v77
	v_exp_f32_e32 v77, v77
	v_mul_f32_e32 v72, 0xbfb8aa3b, v72
	v_exp_f32_e32 v72, v72
	v_mul_f32_e32 v73, 0xbfb8aa3b, v73
	v_add_f32_e32 v78, 1.0, v139
	v_add_f32_e32 v79, 1.0, v140
	v_exp_f32_e32 v73, v73
	v_rcp_f32_e32 v78, v78
	v_rcp_f32_e32 v79, v79
	v_add_f32_e32 v76, 1.0, v76
	v_rcp_f32_e32 v76, v76
	v_add_f32_e32 v77, 1.0, v77
	v_rcp_f32_e32 v77, v77
	v_add_f32_e32 v72, 1.0, v72
	v_rcp_f32_e32 v72, v72
	v_add_f32_e32 v73, 1.0, v73
	v_pk_mul_f32 v[74:75], v[74:75], v[136:137] op_sel_hi:[1,0]
	v_fmac_f32_e32 v137, v78, v138
	v_fmac_f32_e32 v120, v79, v124
	v_lshlrev_b32_e32 v78, 16, v121
	v_lshlrev_b32_e32 v79, 16, v125
	v_rcp_f32_e32 v73, v73
	v_fmac_f32_e32 v78, v76, v79
	v_and_b32_e32 v76, 0xffff0000, v121
	v_and_b32_e32 v79, 0xffff0000, v125
	v_fmac_f32_e32 v76, v77, v79
	v_lshlrev_b32_e32 v77, 16, v122
	v_lshlrev_b32_e32 v79, 16, v126
	v_fmac_f32_e32 v77, v72, v79
	v_and_b32_e32 v72, 0xffff0000, v122
	v_and_b32_e32 v79, 0xffff0000, v126
	v_fmac_f32_e32 v72, v73, v79
	v_mul_f32_e32 v73, 0xbfb8aa3b, v74
	v_exp_f32_e32 v73, v73
	v_mul_f32_e32 v75, 0xbfb8aa3b, v75
	v_pk_mul_f32 v[68:69], v[68:69], v[136:137] op_sel_hi:[1,0]
	v_exp_f32_e32 v75, v75
	v_mul_f32_e32 v68, 0xbfb8aa3b, v68
	v_exp_f32_e32 v68, v68
	v_mul_f32_e32 v69, 0xbfb8aa3b, v69
	v_exp_f32_e32 v69, v69
	v_add_f32_e32 v73, 1.0, v73
	v_rcp_f32_e32 v73, v73
	v_add_f32_e32 v75, 1.0, v75
	v_rcp_f32_e32 v75, v75
	v_add_f32_e32 v68, 1.0, v68
	v_rcp_f32_e32 v68, v68
	v_add_f32_e32 v69, 1.0, v69
	v_lshlrev_b32_e32 v74, 16, v123
	v_lshlrev_b32_e32 v79, 16, v127
	v_rcp_f32_e32 v69, v69
	v_fmac_f32_e32 v74, v73, v79
	v_and_b32_e32 v73, 0xffff0000, v123
	v_and_b32_e32 v79, 0xffff0000, v127
	v_fmac_f32_e32 v73, v75, v79
	s_waitcnt vmcnt(14)
	v_lshlrev_b32_e32 v75, 16, v112
	v_lshlrev_b32_e32 v79, 16, v116
	v_pk_mul_f32 v[70:71], v[70:71], v[136:137] op_sel_hi:[1,0]
	v_fmac_f32_e32 v75, v68, v79
	v_and_b32_e32 v68, 0xffff0000, v112
	v_and_b32_e32 v79, 0xffff0000, v116
	v_fmac_f32_e32 v68, v69, v79
	v_mul_f32_e32 v69, 0xbfb8aa3b, v70
	v_pk_mul_f32 v[64:65], v[64:65], v[136:137] op_sel_hi:[1,0]
	v_exp_f32_e32 v69, v69
	v_mul_f32_e32 v71, 0xbfb8aa3b, v71
	v_exp_f32_e32 v71, v71
	v_mul_f32_e32 v64, 0xbfb8aa3b, v64
	v_exp_f32_e32 v64, v64
	v_mul_f32_e32 v65, 0xbfb8aa3b, v65
	v_exp_f32_e32 v65, v65
	v_add_f32_e32 v69, 1.0, v69
	v_rcp_f32_e32 v69, v69
	v_add_f32_e32 v71, 1.0, v71
	v_rcp_f32_e32 v71, v71
	v_add_f32_e32 v64, 1.0, v64
	v_rcp_f32_e32 v64, v64
	v_add_f32_e32 v65, 1.0, v65
	v_lshlrev_b32_e32 v70, 16, v113
	v_lshlrev_b32_e32 v79, 16, v117
	v_rcp_f32_e32 v65, v65
	v_fmac_f32_e32 v70, v69, v79
	v_and_b32_e32 v69, 0xffff0000, v113
	v_and_b32_e32 v79, 0xffff0000, v117
	v_fmac_f32_e32 v69, v71, v79
	v_lshlrev_b32_e32 v71, 16, v114
	v_lshlrev_b32_e32 v79, 16, v118
	v_pk_mul_f32 v[66:67], v[66:67], v[136:137] op_sel_hi:[1,0]
	v_fmac_f32_e32 v71, v64, v79
	v_and_b32_e32 v79, 0xffff0000, v114
	v_and_b32_e32 v64, 0xffff0000, v118
	v_fmac_f32_e32 v79, v65, v64
	v_mul_f32_e32 v64, 0xbfb8aa3b, v66
	v_exp_f32_e32 v64, v64
	v_mul_f32_e32 v65, 0xbfb8aa3b, v67
	v_exp_f32_e32 v65, v65
	v_lshlrev_b32_e32 v112, 16, v115
	v_add_f32_e32 v64, 1.0, v64
	v_rcp_f32_e32 v64, v64
	v_add_f32_e32 v65, 1.0, v65
	v_rcp_f32_e32 v65, v65
	v_lshlrev_b32_e32 v66, 16, v119
	v_fmac_f32_e32 v112, v64, v66
	v_and_b32_e32 v113, 0xffff0000, v115
	v_and_b32_e32 v64, 0xffff0000, v119
	v_fmac_f32_e32 v113, v65, v64
	v_cvt_pk_bf16_f32 v64, v137, v120
	v_cvt_pk_bf16_f32 v65, v78, v76
	v_cvt_pk_bf16_f32 v66, v77, v72
	v_cvt_pk_bf16_f32 v67, v74, v73
	global_store_dwordx4 v[200:201], v[64:67], off
	v_lshlrev_b32_e32 v72, 16, v64
	s_nop 0
	v_and_b32_e32 v64, 0xffff0000, v64
	v_mul_f32_e32 v64, v64, v64
	v_fmac_f32_e32 v64, v72, v72
	v_lshlrev_b32_e32 v72, 16, v65
	v_and_b32_e32 v65, 0xffff0000, v65
	v_mul_f32_e32 v65, v65, v65
	v_fmac_f32_e32 v65, v72, v72
	v_add_f32_e32 v64, v64, v65
	v_lshlrev_b32_e32 v65, 16, v66
	v_and_b32_e32 v66, 0xffff0000, v66
	v_mul_f32_e32 v66, v66, v66
	v_fmac_f32_e32 v66, v65, v65
	v_add_f32_e32 v64, v64, v66
	v_and_b32_e32 v66, 0xffff0000, v67
	v_lshlrev_b32_e32 v65, 16, v67
	v_mul_f32_e32 v66, v66, v66
	v_fmac_f32_e32 v66, v65, v65
	v_add_f32_e32 v64, v64, v66
	v_cvt_pk_bf16_f32 v66, v75, v68
	v_cvt_pk_bf16_f32 v67, v70, v69
	v_cvt_pk_bf16_f32 v68, v71, v79
	v_cvt_pk_bf16_f32 v69, v112, v113
	global_store_dwordx4 v[198:199], v[66:69], off
	v_and_b32_e32 v70, 0xffff0000, v66
	v_lshlrev_b32_e32 v65, 16, v66
	v_mul_f32_e32 v70, v70, v70
	v_fmac_f32_e32 v70, v65, v65
	v_add_f32_e32 v64, v64, v70
	v_and_b32_e32 v70, 0xffff0000, v67
	v_lshlrev_b32_e32 v65, 16, v67
	v_mul_f32_e32 v70, v70, v70
	v_fmac_f32_e32 v70, v65, v65
	v_add_f32_e32 v64, v64, v70
	v_and_b32_e32 v70, 0xffff0000, v68
	v_lshlrev_b32_e32 v65, 16, v68
	v_mul_f32_e32 v70, v70, v70
	v_fmac_f32_e32 v70, v65, v65
	v_add_f32_e32 v64, v64, v70
	v_and_b32_e32 v70, 0xffff0000, v69
	v_lshlrev_b32_e32 v65, 16, v69
	v_mul_f32_e32 v70, v70, v70
	v_fmac_f32_e32 v70, v65, v65
	v_add_f32_e32 v64, v64, v70
	v_mov_b32_e32 v65, v64
	s_nop 1
	v_permlane16_swap_b32_e32 v65, v64
	s_nop 1
	s_waitcnt lgkmcnt(0)
	v_add_f32_e32 v64, v64, v65
	v_mov_b32_e32 v65, v64
	s_nop 1
	v_permlane32_swap_b32_e32 v65, v64
	s_nop 1
	s_and_saveexec_b64 s[12:13], vcc
	s_cbranch_execz .LBB0_246
	s_waitcnt lgkmcnt(0)
	v_add_f32_e32 v64, v64, v65
	v_mul_f32_e32 v64, 0x49800000, v64
	v_trunc_f32_e32 v64, v64
	v_mul_f32_e32 v65, 0x2f800000, v64
	v_floor_f32_e32 v65, v65
	v_fmac_f32_e32 v64, 0xcf800000, v65
	v_cvt_u32_f32_e32 v64, v64
	v_cvt_u32_f32_e32 v65, v65
	global_atomic_add_x2 v[192:193], v[64:65], off offset:384
.LBB0_246:
	s_or_b64 exec, exec, s[12:13]
	v_ffbh_u32_e32 v64, v195
	v_min_u32_e32 v66, 32, v64
	s_waitcnt lgkmcnt(0)
	v_lshlrev_b64 v[64:65], v66, v[194:195]
	v_min_u32_e32 v64, 1, v64
	v_or_b32_e32 v64, v65, v64
	v_cvt_f32_u32_e32 v64, v64
	v_sub_u32_e32 v65, 32, v66
	s_waitcnt vmcnt(11)
	v_lshlrev_b32_e32 v112, 16, v104
	v_and_b32_e32 v104, 0xffff0000, v104
	v_ldexp_f32 v64, v64, v65
	v_fmamk_f32 v64, v64, 0x30800000, v223
	v_rsq_f32_e32 v64, v64
	s_waitcnt vmcnt(9)
	v_and_b32_e32 v113, 0xffff0000, v96
	v_lshlrev_b32_e32 v114, 16, v97
	v_and_b32_e32 v115, 0xffff0000, v97
	v_pk_mul_f32 v[60:61], v[60:61], v[64:65] op_sel_hi:[1,0]
	v_pk_mul_f32 v[62:63], v[62:63], v[64:65] op_sel_hi:[1,0]
	v_mul_f32_e32 v60, 0xbfb8aa3b, v60
	v_exp_f32_e32 v60, v60
	v_mul_f32_e32 v61, 0xbfb8aa3b, v61
	v_exp_f32_e32 v61, v61
	v_pk_mul_f32 v[58:59], v[58:59], v[64:65] op_sel_hi:[1,0]
	v_add_f32_e32 v60, 1.0, v60
	v_rcp_f32_e32 v60, v60
	v_add_f32_e32 v61, 1.0, v61
	v_rcp_f32_e32 v61, v61
	v_pk_mul_f32 v[56:57], v[56:57], v[64:65] op_sel_hi:[1,0]
	s_waitcnt vmcnt(7)
; #define EP_LOAD(q) do { _Pragma("unroll") for (int bj = 0; bj < 2; ++bj) { const unsigned o = ER_OFF(q, bj); t[(q) & 1][bj] = *(const u32x4*)(base + o); pw[(q) & 1][bj] = *(const u32x4*)(pp + o); } } while (0)
;     __device__ __forceinline__ void operator()(f32x4 (&acc)[2][2][4][2], const Unit& u, int wr, int wc, int fr, int fq) const {
;     ...
;         bf16_t* hb = pp;
;         EP_LOAD(0); EP_LOAD(1); EP_ADD(0); EP_ADD(1);
; #pragma unroll
;         for (int q = 0; q < 8; q += 2) { if (q < 6) { EP_LOAD(q + 2); EP_LOAD(q + 3); } ER_STORE(q); ER_STORE(q + 1); if (q < 6) { EP_ADD(q + 2); EP_ADD(q + 3); } }
	v_lshlrev_b32_e32 v65, 16, v108
	v_fmac_f32_e32 v112, v60, v65
	v_and_b32_e32 v60, 0xffff0000, v108
	v_fmac_f32_e32 v104, v61, v60
	v_mul_f32_e32 v61, 0xbfb8aa3b, v62
	v_exp_f32_e32 v61, v61
	v_lshlrev_b32_e32 v108, 16, v105
	v_lshlrev_b32_e32 v60, 16, v109
	v_mul_f32_e32 v56, 0xbfb8aa3b, v56
	v_add_f32_e32 v61, 1.0, v61
	v_rcp_f32_e32 v61, v61
	v_exp_f32_e32 v56, v56
	v_mul_f32_e32 v57, 0xbfb8aa3b, v57
	v_exp_f32_e32 v57, v57
	v_fmac_f32_e32 v108, v61, v60
	v_mul_f32_e32 v61, 0xbfb8aa3b, v63
	v_exp_f32_e32 v61, v61
	v_add_f32_e32 v56, 1.0, v56
	v_rcp_f32_e32 v56, v56
	v_add_f32_e32 v57, 1.0, v57
	v_add_f32_e32 v61, 1.0, v61
	v_rcp_f32_e32 v61, v61
	v_rcp_f32_e32 v57, v57
	v_and_b32_e32 v105, 0xffff0000, v105
	v_and_b32_e32 v60, 0xffff0000, v109
	v_fmac_f32_e32 v105, v61, v60
	v_lshlrev_b32_e32 v109, 16, v106
	v_lshlrev_b32_e32 v60, 16, v110
	v_fmac_f32_e32 v109, v56, v60
	v_and_b32_e32 v106, 0xffff0000, v106
	v_and_b32_e32 v56, 0xffff0000, v110
	v_fmac_f32_e32 v106, v57, v56
	v_mul_f32_e32 v57, 0xbfb8aa3b, v58
	v_exp_f32_e32 v57, v57
	v_lshlrev_b32_e32 v110, 16, v107
	v_lshlrev_b32_e32 v56, 16, v111
	v_pk_mul_f32 v[52:53], v[52:53], v[64:65] op_sel_hi:[1,0]
	v_add_f32_e32 v57, 1.0, v57
	v_rcp_f32_e32 v57, v57
	v_mul_f32_e32 v52, 0xbfb8aa3b, v52
	v_exp_f32_e32 v52, v52
	v_mul_f32_e32 v53, 0xbfb8aa3b, v53
	v_fmac_f32_e32 v110, v57, v56
	v_mul_f32_e32 v57, 0xbfb8aa3b, v59
	v_exp_f32_e32 v57, v57
	v_exp_f32_e32 v53, v53
	v_add_f32_e32 v52, 1.0, v52
	v_rcp_f32_e32 v52, v52
	v_add_f32_e32 v57, 1.0, v57
	v_rcp_f32_e32 v57, v57
	v_add_f32_e32 v53, 1.0, v53
	v_rcp_f32_e32 v53, v53
	v_and_b32_e32 v107, 0xffff0000, v107
	v_and_b32_e32 v56, 0xffff0000, v111
	v_fmac_f32_e32 v107, v57, v56
	v_lshlrev_b32_e32 v111, 16, v96
	v_lshlrev_b32_e32 v56, 16, v100
	v_pk_mul_f32 v[54:55], v[54:55], v[64:65] op_sel_hi:[1,0]
	v_fmac_f32_e32 v111, v52, v56
	v_and_b32_e32 v52, 0xffff0000, v100
	v_fmac_f32_e32 v113, v53, v52
	v_mul_f32_e32 v53, 0xbfb8aa3b, v54
	v_exp_f32_e32 v53, v53
	v_lshlrev_b32_e32 v52, 16, v101
	v_pk_mul_f32 v[48:49], v[48:49], v[64:65] op_sel_hi:[1,0]
	v_lshlrev_b32_e32 v116, 16, v98
	v_add_f32_e32 v53, 1.0, v53
	v_rcp_f32_e32 v53, v53
	v_mul_f32_e32 v48, 0xbfb8aa3b, v48
	v_exp_f32_e32 v48, v48
	v_mul_f32_e32 v49, 0xbfb8aa3b, v49
	v_fmac_f32_e32 v114, v53, v52
	v_mul_f32_e32 v53, 0xbfb8aa3b, v55
	v_exp_f32_e32 v53, v53
	v_exp_f32_e32 v49, v49
	v_add_f32_e32 v48, 1.0, v48
	v_rcp_f32_e32 v48, v48
	v_add_f32_e32 v53, 1.0, v53
	v_rcp_f32_e32 v53, v53
	v_add_f32_e32 v49, 1.0, v49
	v_rcp_f32_e32 v49, v49
	v_and_b32_e32 v52, 0xffff0000, v101
	v_fmac_f32_e32 v115, v53, v52
	v_lshlrev_b32_e32 v52, 16, v102
	v_pk_mul_f32 v[50:51], v[50:51], v[64:65] op_sel_hi:[1,0]
	v_fmac_f32_e32 v116, v48, v52
	v_and_b32_e32 v117, 0xffff0000, v98
	v_and_b32_e32 v48, 0xffff0000, v102
	v_fmac_f32_e32 v117, v49, v48
	v_mul_f32_e32 v49, 0xbfb8aa3b, v50
	v_exp_f32_e32 v49, v49
	v_lshlrev_b32_e32 v118, 16, v99
	v_lshlrev_b32_e32 v48, 16, v103
	v_and_b32_e32 v119, 0xffff0000, v99
	v_add_f32_e32 v49, 1.0, v49
	v_rcp_f32_e32 v49, v49
	v_add_u32_e32 v168, 0x28000, v190
	v_fmac_f32_e32 v118, v49, v48
	v_mul_f32_e32 v49, 0xbfb8aa3b, v51
	v_exp_f32_e32 v49, v49
	v_and_b32_e32 v48, 0xffff0000, v103
	v_add_f32_e32 v49, 1.0, v49
	v_rcp_f32_e32 v49, v49
	s_nop 0
	v_fmac_f32_e32 v119, v49, v48
	v_lshlrev_b64 v[48:49], 1, v[168:169]
	v_add_u32_e32 v168, 0x28080, v190
	v_lshl_add_u64 v[50:51], s[70:71], 0, v[48:49]
	v_lshl_add_u64 v[102:103], s[20:21], 0, v[48:49]
	v_lshlrev_b64 v[48:49], 1, v[168:169]
	v_lshl_add_u64 v[100:101], s[20:21], 0, v[48:49]
	v_add_u32_e32 v168, 0x2c000, v190
	global_load_dwordx4 v[72:75], v[50:51], off
	global_load_dwordx4 v[68:71], v[100:101], off
	v_lshl_add_u64 v[50:51], s[70:71], 0, v[48:49]
	v_lshlrev_b64 v[48:49], 1, v[168:169]
	v_add_u32_e32 v168, 0x2c080, v190
	v_lshl_add_u64 v[98:99], s[20:21], 0, v[48:49]
	v_lshlrev_b64 v[52:53], 1, v[168:169]
	global_load_dwordx4 v[64:67], v[50:51], off
	global_load_dwordx4 v[60:63], v[98:99], off
	v_lshl_add_u64 v[50:51], s[70:71], 0, v[48:49]
	v_lshl_add_u64 v[48:49], s[70:71], 0, v[52:53]
	v_lshl_add_u64 v[96:97], s[20:21], 0, v[52:53]
	global_load_dwordx4 v[76:79], v[102:103], off
	global_load_dwordx4 v[56:59], v[50:51], off
	global_load_dwordx4 v[52:55], v[96:97], off
	s_nop 0
	global_load_dwordx4 v[48:51], v[48:49], off
	v_cvt_pk_bf16_f32 v104, v112, v104
	v_cvt_pk_bf16_f32 v105, v108, v105
	v_cvt_pk_bf16_f32 v106, v109, v106
	v_cvt_pk_bf16_f32 v107, v110, v107
	global_store_dwordx4 v[134:135], v[104:107], off
	v_lshlrev_b32_e32 v108, 16, v104
	s_nop 0
	v_and_b32_e32 v104, 0xffff0000, v104
	v_mul_f32_e32 v104, v104, v104
	v_fmac_f32_e32 v104, v108, v108
	v_lshlrev_b32_e32 v108, 16, v105
	v_and_b32_e32 v105, 0xffff0000, v105
	v_mul_f32_e32 v105, v105, v105
	v_fmac_f32_e32 v105, v108, v108
	v_add_f32_e32 v104, v104, v105
	v_lshlrev_b32_e32 v105, 16, v106
	v_and_b32_e32 v106, 0xffff0000, v106
	v_mul_f32_e32 v106, v106, v106
	v_fmac_f32_e32 v106, v105, v105
	v_add_f32_e32 v104, v104, v106
	v_and_b32_e32 v106, 0xffff0000, v107
	v_lshlrev_b32_e32 v105, 16, v107
	v_mul_f32_e32 v106, v106, v106
	v_fmac_f32_e32 v106, v105, v105
	v_add_f32_e32 v108, v104, v106
	v_cvt_pk_bf16_f32 v104, v111, v113
	v_cvt_pk_bf16_f32 v105, v114, v115
	v_cvt_pk_bf16_f32 v106, v116, v117
	v_cvt_pk_bf16_f32 v107, v118, v119
	global_store_dwordx4 v[132:133], v[104:107], off
	v_lshlrev_b32_e32 v109, 16, v104
	s_nop 0
	v_and_b32_e32 v104, 0xffff0000, v104
	v_mul_f32_e32 v104, v104, v104
	v_fmac_f32_e32 v104, v109, v109
	v_add_f32_e32 v104, v108, v104
	v_lshlrev_b32_e32 v108, 16, v105
	v_and_b32_e32 v105, 0xffff0000, v105
	v_mul_f32_e32 v105, v105, v105
	v_fmac_f32_e32 v105, v108, v108
	v_add_f32_e32 v104, v104, v105
	v_lshlrev_b32_e32 v105, 16, v106
	v_and_b32_e32 v106, 0xffff0000, v106
	v_mul_f32_e32 v106, v106, v106
	v_fmac_f32_e32 v106, v105, v105
	v_add_f32_e32 v104, v104, v106
	v_and_b32_e32 v106, 0xffff0000, v107
	v_lshlrev_b32_e32 v105, 16, v107
	v_mul_f32_e32 v106, v106, v106
	v_fmac_f32_e32 v106, v105, v105
	v_add_f32_e32 v104, v104, v106
	v_mov_b32_e32 v105, v104
	s_nop 1
	v_permlane16_swap_b32_e32 v105, v104
	s_nop 1
	s_waitcnt lgkmcnt(0)
	v_add_f32_e32 v104, v104, v105
	v_mov_b32_e32 v105, v104
	s_nop 1
	v_permlane32_swap_b32_e32 v105, v104
	s_nop 1
	s_and_saveexec_b64 s[12:13], vcc
	s_cbranch_execz .LBB0_248
	s_waitcnt lgkmcnt(0)
	v_add_f32_e32 v104, v104, v105
	v_mul_f32_e32 v104, 0x49800000, v104
	v_trunc_f32_e32 v104, v104
	v_mul_f32_e32 v105, 0x2f800000, v104
	v_floor_f32_e32 v105, v105
	v_fmac_f32_e32 v104, 0xcf800000, v105
	v_cvt_u32_f32_e32 v104, v104
	v_cvt_u32_f32_e32 v105, v105
	global_atomic_add_x2 v[192:193], v[104:105], off offset:1024
; #define EP_LOAD(q) do { _Pragma("unroll") for (int bj = 0; bj < 2; ++bj) { const unsigned o = ER_OFF(q, bj); t[(q) & 1][bj] = *(const u32x4*)(base + o); pw[(q) & 1][bj] = *(const u32x4*)(pp + o); } } while (0)
;     __device__ __forceinline__ void operator()(f32x4 (&acc)[2][2][4][2], const Unit& u, int wr, int wc, int fr, int fq) const {
;     ...
;         bf16_t* hb = pp;
;         EP_LOAD(0); EP_LOAD(1); EP_ADD(0); EP_ADD(1);
; #pragma unroll
;         for (int q = 0; q < 8; q += 2) { if (q < 6) { EP_LOAD(q + 2); EP_LOAD(q + 3); } ER_STORE(q); ER_STORE(q + 1); if (q < 6) { EP_ADD(q + 2); EP_ADD(q + 3); } }
.LBB0_248:
	s_or_b64 exec, exec, s[12:13]
	v_ffbh_u32_e32 v104, v189
	v_min_u32_e32 v106, 32, v104
	s_waitcnt lgkmcnt(0)
	v_lshlrev_b64 v[104:105], v106, v[188:189]
	v_min_u32_e32 v104, 1, v104
	v_or_b32_e32 v104, v105, v104
	v_cvt_f32_u32_e32 v104, v104
	v_sub_u32_e32 v105, 32, v106
	v_lshlrev_b32_e32 v106, 16, v92
	v_and_b32_e32 v92, 0xffff0000, v92
	v_ldexp_f32 v104, v104, v105
	v_fmamk_f32 v104, v104, 0x30800000, v223
	v_rsq_f32_e32 v104, v104
	s_waitcnt vmcnt(16)
	v_lshlrev_b32_e32 v105, 16, v88
	v_and_b32_e32 v88, 0xffff0000, v88
	v_pk_mul_f32 v[44:45], v[44:45], v[104:105] op_sel_hi:[1,0]
	s_nop 0
	v_mul_f32_e32 v44, 0xbfb8aa3b, v44
	v_mul_f32_e32 v45, 0xbfb8aa3b, v45
	v_exp_f32_e32 v107, v44
	v_exp_f32_e32 v108, v45
	v_pk_mul_f32 v[44:45], v[46:47], v[104:105] op_sel_hi:[1,0]
	v_pk_mul_f32 v[40:41], v[40:41], v[104:105] op_sel_hi:[1,0]
	v_mul_f32_e32 v44, 0xbfb8aa3b, v44
	v_exp_f32_e32 v44, v44
	v_mul_f32_e32 v45, 0xbfb8aa3b, v45
	v_exp_f32_e32 v45, v45
	v_mul_f32_e32 v40, 0xbfb8aa3b, v40
	v_exp_f32_e32 v40, v40
	v_mul_f32_e32 v41, 0xbfb8aa3b, v41
	v_add_f32_e32 v46, 1.0, v107
	v_add_f32_e32 v47, 1.0, v108
	v_exp_f32_e32 v41, v41
	v_rcp_f32_e32 v46, v46
	v_rcp_f32_e32 v47, v47
	v_add_f32_e32 v44, 1.0, v44
	v_rcp_f32_e32 v44, v44
	v_add_f32_e32 v45, 1.0, v45
	v_rcp_f32_e32 v45, v45
	v_add_f32_e32 v40, 1.0, v40
	v_rcp_f32_e32 v40, v40
	v_add_f32_e32 v41, 1.0, v41
	v_pk_mul_f32 v[42:43], v[42:43], v[104:105] op_sel_hi:[1,0]
	v_fmac_f32_e32 v105, v46, v106
	v_fmac_f32_e32 v88, v47, v92
	v_lshlrev_b32_e32 v46, 16, v89
	v_lshlrev_b32_e32 v47, 16, v93
	v_rcp_f32_e32 v41, v41
	v_fmac_f32_e32 v46, v44, v47
	v_and_b32_e32 v44, 0xffff0000, v89
	v_and_b32_e32 v47, 0xffff0000, v93
	v_fmac_f32_e32 v44, v45, v47
	v_lshlrev_b32_e32 v45, 16, v90
	v_lshlrev_b32_e32 v47, 16, v94
	v_fmac_f32_e32 v45, v40, v47
	v_and_b32_e32 v40, 0xffff0000, v90
	v_and_b32_e32 v47, 0xffff0000, v94
	v_fmac_f32_e32 v40, v41, v47
	v_mul_f32_e32 v41, 0xbfb8aa3b, v42
	v_exp_f32_e32 v41, v41
	v_mul_f32_e32 v43, 0xbfb8aa3b, v43
	v_pk_mul_f32 v[36:37], v[36:37], v[104:105] op_sel_hi:[1,0]
	v_exp_f32_e32 v43, v43
	v_mul_f32_e32 v36, 0xbfb8aa3b, v36
	v_exp_f32_e32 v36, v36
	v_mul_f32_e32 v37, 0xbfb8aa3b, v37
	v_exp_f32_e32 v37, v37
	v_add_f32_e32 v41, 1.0, v41
	v_rcp_f32_e32 v41, v41
	v_add_f32_e32 v43, 1.0, v43
	v_rcp_f32_e32 v43, v43
	v_add_f32_e32 v36, 1.0, v36
	v_rcp_f32_e32 v36, v36
	v_add_f32_e32 v37, 1.0, v37
	v_lshlrev_b32_e32 v42, 16, v91
	v_lshlrev_b32_e32 v47, 16, v95
	v_rcp_f32_e32 v37, v37
	v_fmac_f32_e32 v42, v41, v47
	v_and_b32_e32 v41, 0xffff0000, v91
	v_and_b32_e32 v47, 0xffff0000, v95
	v_fmac_f32_e32 v41, v43, v47
	s_waitcnt vmcnt(14)
	v_lshlrev_b32_e32 v43, 16, v80
	v_lshlrev_b32_e32 v47, 16, v84
	v_pk_mul_f32 v[38:39], v[38:39], v[104:105] op_sel_hi:[1,0]
	v_fmac_f32_e32 v43, v36, v47
	v_and_b32_e32 v36, 0xffff0000, v80
	v_and_b32_e32 v47, 0xffff0000, v84
	v_fmac_f32_e32 v36, v37, v47
	v_mul_f32_e32 v37, 0xbfb8aa3b, v38
	v_pk_mul_f32 v[32:33], v[32:33], v[104:105] op_sel_hi:[1,0]
	v_exp_f32_e32 v37, v37
	v_mul_f32_e32 v39, 0xbfb8aa3b, v39
	v_exp_f32_e32 v39, v39
	v_mul_f32_e32 v32, 0xbfb8aa3b, v32
	v_exp_f32_e32 v32, v32
	v_mul_f32_e32 v33, 0xbfb8aa3b, v33
	v_exp_f32_e32 v33, v33
	v_add_f32_e32 v37, 1.0, v37
	v_rcp_f32_e32 v37, v37
	v_add_f32_e32 v39, 1.0, v39
	v_rcp_f32_e32 v39, v39
	v_add_f32_e32 v32, 1.0, v32
	v_rcp_f32_e32 v32, v32
	v_add_f32_e32 v33, 1.0, v33
	v_lshlrev_b32_e32 v38, 16, v81
	v_lshlrev_b32_e32 v47, 16, v85
	v_rcp_f32_e32 v33, v33
	v_fmac_f32_e32 v38, v37, v47
	v_and_b32_e32 v37, 0xffff0000, v81
	v_and_b32_e32 v47, 0xffff0000, v85
	v_fmac_f32_e32 v37, v39, v47
	v_lshlrev_b32_e32 v39, 16, v82
	v_lshlrev_b32_e32 v47, 16, v86
	v_pk_mul_f32 v[34:35], v[34:35], v[104:105] op_sel_hi:[1,0]
	v_fmac_f32_e32 v39, v32, v47
	v_and_b32_e32 v47, 0xffff0000, v82
	v_and_b32_e32 v32, 0xffff0000, v86
	v_fmac_f32_e32 v47, v33, v32
	v_mul_f32_e32 v32, 0xbfb8aa3b, v34
	v_exp_f32_e32 v32, v32
	v_mul_f32_e32 v33, 0xbfb8aa3b, v35
	v_exp_f32_e32 v33, v33
	v_lshlrev_b32_e32 v80, 16, v83
	v_add_f32_e32 v32, 1.0, v32
	v_rcp_f32_e32 v32, v32
	v_add_f32_e32 v33, 1.0, v33
	v_rcp_f32_e32 v33, v33
	v_lshlrev_b32_e32 v34, 16, v87
	v_fmac_f32_e32 v80, v32, v34
	v_and_b32_e32 v81, 0xffff0000, v83
	v_and_b32_e32 v32, 0xffff0000, v87
	v_fmac_f32_e32 v81, v33, v32
	v_cvt_pk_bf16_f32 v32, v105, v88
	v_cvt_pk_bf16_f32 v33, v46, v44
	v_cvt_pk_bf16_f32 v34, v45, v40
	v_cvt_pk_bf16_f32 v35, v42, v41
	global_store_dwordx4 v[130:131], v[32:35], off
	v_lshlrev_b32_e32 v40, 16, v32
	s_nop 0
	v_and_b32_e32 v32, 0xffff0000, v32
	v_mul_f32_e32 v32, v32, v32
	v_fmac_f32_e32 v32, v40, v40
	v_lshlrev_b32_e32 v40, 16, v33
	v_and_b32_e32 v33, 0xffff0000, v33
	v_mul_f32_e32 v33, v33, v33
	v_fmac_f32_e32 v33, v40, v40
	v_add_f32_e32 v32, v32, v33
	v_lshlrev_b32_e32 v33, 16, v34
	v_and_b32_e32 v34, 0xffff0000, v34
	v_mul_f32_e32 v34, v34, v34
	v_fmac_f32_e32 v34, v33, v33
	v_add_f32_e32 v32, v32, v34
	v_and_b32_e32 v34, 0xffff0000, v35
	v_lshlrev_b32_e32 v33, 16, v35
	v_mul_f32_e32 v34, v34, v34
	v_fmac_f32_e32 v34, v33, v33
	v_add_f32_e32 v32, v32, v34
	v_cvt_pk_bf16_f32 v34, v43, v36
	v_cvt_pk_bf16_f32 v35, v38, v37
	v_cvt_pk_bf16_f32 v36, v39, v47
	v_cvt_pk_bf16_f32 v37, v80, v81
	global_store_dwordx4 v[128:129], v[34:37], off
	v_and_b32_e32 v38, 0xffff0000, v34
	v_lshlrev_b32_e32 v33, 16, v34
	v_mul_f32_e32 v38, v38, v38
	v_fmac_f32_e32 v38, v33, v33
	v_add_f32_e32 v32, v32, v38
	v_and_b32_e32 v38, 0xffff0000, v35
	v_lshlrev_b32_e32 v33, 16, v35
	v_mul_f32_e32 v38, v38, v38
	v_fmac_f32_e32 v38, v33, v33
	v_add_f32_e32 v32, v32, v38
	v_and_b32_e32 v38, 0xffff0000, v36
	v_lshlrev_b32_e32 v33, 16, v36
	v_mul_f32_e32 v38, v38, v38
	v_fmac_f32_e32 v38, v33, v33
	v_add_f32_e32 v32, v32, v38
	v_and_b32_e32 v38, 0xffff0000, v37
	v_lshlrev_b32_e32 v33, 16, v37
	v_mul_f32_e32 v38, v38, v38
	v_fmac_f32_e32 v38, v33, v33
	v_add_f32_e32 v32, v32, v38
	v_mov_b32_e32 v33, v32
	s_nop 1
	v_permlane16_swap_b32_e32 v33, v32
	s_nop 1
	s_waitcnt lgkmcnt(0)
	v_add_f32_e32 v32, v32, v33
	v_mov_b32_e32 v33, v32
	s_nop 1
	v_permlane32_swap_b32_e32 v33, v32
	s_nop 1
	s_and_saveexec_b64 s[12:13], vcc
	s_cbranch_execz .LBB0_250
	s_waitcnt lgkmcnt(0)
	v_add_f32_e32 v32, v32, v33
	v_mul_f32_e32 v32, 0x49800000, v32
	v_trunc_f32_e32 v32, v32
	v_mul_f32_e32 v33, 0x2f800000, v32
	v_floor_f32_e32 v33, v33
	v_fmac_f32_e32 v32, 0xcf800000, v33
	v_cvt_u32_f32_e32 v32, v32
	v_cvt_u32_f32_e32 v33, v33
	global_atomic_add_x2 v[192:193], v[32:33], off offset:1152
; #define EP_LOAD(q) do { _Pragma("unroll") for (int bj = 0; bj < 2; ++bj) { const unsigned o = ER_OFF(q, bj); t[(q) & 1][bj] = *(const u32x4*)(base + o); pw[(q) & 1][bj] = *(const u32x4*)(pp + o); } } while (0)
;     __device__ __forceinline__ void operator()(f32x4 (&acc)[2][2][4][2], const Unit& u, int wr, int wc, int fr, int fq) const {
;     ...
;         bf16_t* hb = pp;
;         EP_LOAD(0); EP_LOAD(1); EP_ADD(0); EP_ADD(1);
; #pragma unroll
;         for (int q = 0; q < 8; q += 2) { if (q < 6) { EP_LOAD(q + 2); EP_LOAD(q + 3); } ER_STORE(q); ER_STORE(q + 1); if (q < 6) { EP_ADD(q + 2); EP_ADD(q + 3); } }
.LBB0_250:
	s_or_b64 exec, exec, s[12:13]
	v_ffbh_u32_e32 v32, v187
	v_min_u32_e32 v34, 32, v32
	s_waitcnt lgkmcnt(0)
	v_lshlrev_b64 v[32:33], v34, v[186:187]
	v_min_u32_e32 v32, 1, v32
	v_or_b32_e32 v32, v33, v32
	v_cvt_f32_u32_e32 v32, v32
	v_sub_u32_e32 v33, 32, v34
	s_waitcnt vmcnt(7)
	v_lshlrev_b32_e32 v34, 16, v76
	v_and_b32_e32 v35, 0xffff0000, v72
	v_ldexp_f32 v32, v32, v33
	v_fmamk_f32 v32, v32, 0x30800000, v223
	v_rsq_f32_e32 v32, v32
	v_lshlrev_b32_e32 v33, 16, v72
	v_and_b32_e32 v38, 0xffff0000, v76
	v_pk_mul_f32 v[28:29], v[28:29], v[32:33] op_sel_hi:[1,0]
	s_nop 0
	v_mul_f32_e32 v28, 0xbfb8aa3b, v28
	v_mul_f32_e32 v29, 0xbfb8aa3b, v29
	v_exp_f32_e32 v36, v28
	v_exp_f32_e32 v37, v29
	v_pk_mul_f32 v[28:29], v[30:31], v[32:33] op_sel_hi:[1,0]
	v_pk_mul_f32 v[24:25], v[24:25], v[32:33] op_sel_hi:[1,0]
	v_mul_f32_e32 v28, 0xbfb8aa3b, v28
	v_exp_f32_e32 v28, v28
	v_mul_f32_e32 v29, 0xbfb8aa3b, v29
	v_exp_f32_e32 v29, v29
	v_mul_f32_e32 v24, 0xbfb8aa3b, v24
	v_exp_f32_e32 v24, v24
	v_mul_f32_e32 v25, 0xbfb8aa3b, v25
	v_add_f32_e32 v30, 1.0, v36
	v_add_f32_e32 v31, 1.0, v37
	v_exp_f32_e32 v25, v25
	v_rcp_f32_e32 v30, v30
	v_rcp_f32_e32 v31, v31
	v_add_f32_e32 v28, 1.0, v28
	v_rcp_f32_e32 v28, v28
	v_add_f32_e32 v29, 1.0, v29
	v_rcp_f32_e32 v29, v29
	v_add_f32_e32 v24, 1.0, v24
	v_rcp_f32_e32 v24, v24
	v_add_f32_e32 v25, 1.0, v25
	v_pk_mul_f32 v[26:27], v[26:27], v[32:33] op_sel_hi:[1,0]
	v_fmac_f32_e32 v33, v30, v34
	v_fmac_f32_e32 v35, v31, v38
	v_lshlrev_b32_e32 v30, 16, v73
	v_lshlrev_b32_e32 v31, 16, v77
	v_rcp_f32_e32 v25, v25
	v_fmac_f32_e32 v30, v28, v31
	v_and_b32_e32 v28, 0xffff0000, v73
	v_and_b32_e32 v31, 0xffff0000, v77
	v_fmac_f32_e32 v28, v29, v31
	v_lshlrev_b32_e32 v29, 16, v74
	v_lshlrev_b32_e32 v31, 16, v78
	v_fmac_f32_e32 v29, v24, v31
	v_and_b32_e32 v24, 0xffff0000, v74
	v_and_b32_e32 v31, 0xffff0000, v78
	v_fmac_f32_e32 v24, v25, v31
	v_mul_f32_e32 v25, 0xbfb8aa3b, v26
	v_exp_f32_e32 v25, v25
	v_mul_f32_e32 v27, 0xbfb8aa3b, v27
	v_pk_mul_f32 v[20:21], v[20:21], v[32:33] op_sel_hi:[1,0]
	v_exp_f32_e32 v27, v27
	v_mul_f32_e32 v20, 0xbfb8aa3b, v20
	v_exp_f32_e32 v20, v20
	v_mul_f32_e32 v21, 0xbfb8aa3b, v21
	v_exp_f32_e32 v21, v21
	v_add_f32_e32 v25, 1.0, v25
	v_rcp_f32_e32 v25, v25
	v_add_f32_e32 v27, 1.0, v27
	v_rcp_f32_e32 v27, v27
	v_add_f32_e32 v20, 1.0, v20
	v_rcp_f32_e32 v20, v20
	v_add_f32_e32 v21, 1.0, v21
	v_lshlrev_b32_e32 v26, 16, v75
	v_lshlrev_b32_e32 v31, 16, v79
	v_rcp_f32_e32 v21, v21
	v_fmac_f32_e32 v26, v25, v31
	v_and_b32_e32 v25, 0xffff0000, v75
	v_and_b32_e32 v31, 0xffff0000, v79
	v_fmac_f32_e32 v25, v27, v31
	v_lshlrev_b32_e32 v27, 16, v64
	v_lshlrev_b32_e32 v31, 16, v68
	v_pk_mul_f32 v[22:23], v[22:23], v[32:33] op_sel_hi:[1,0]
	v_fmac_f32_e32 v27, v20, v31
	v_and_b32_e32 v20, 0xffff0000, v64
	v_and_b32_e32 v31, 0xffff0000, v68
	v_fmac_f32_e32 v20, v21, v31
	v_mul_f32_e32 v21, 0xbfb8aa3b, v22
	v_pk_mul_f32 v[16:17], v[16:17], v[32:33] op_sel_hi:[1,0]
	v_exp_f32_e32 v21, v21
	v_mul_f32_e32 v23, 0xbfb8aa3b, v23
	v_exp_f32_e32 v23, v23
	v_mul_f32_e32 v16, 0xbfb8aa3b, v16
	v_exp_f32_e32 v16, v16
	v_mul_f32_e32 v17, 0xbfb8aa3b, v17
	v_exp_f32_e32 v17, v17
	v_add_f32_e32 v21, 1.0, v21
	v_rcp_f32_e32 v21, v21
	v_add_f32_e32 v23, 1.0, v23
	v_rcp_f32_e32 v23, v23
	v_add_f32_e32 v16, 1.0, v16
	v_rcp_f32_e32 v16, v16
	v_add_f32_e32 v17, 1.0, v17
	v_lshlrev_b32_e32 v22, 16, v65
	v_lshlrev_b32_e32 v31, 16, v69
	v_rcp_f32_e32 v17, v17
	v_fmac_f32_e32 v22, v21, v31
	v_and_b32_e32 v21, 0xffff0000, v65
	v_and_b32_e32 v31, 0xffff0000, v69
	v_fmac_f32_e32 v21, v23, v31
	v_lshlrev_b32_e32 v23, 16, v66
	v_lshlrev_b32_e32 v31, 16, v70
	v_pk_mul_f32 v[18:19], v[18:19], v[32:33] op_sel_hi:[1,0]
	v_fmac_f32_e32 v23, v16, v31
	v_and_b32_e32 v31, 0xffff0000, v66
	v_and_b32_e32 v16, 0xffff0000, v70
	v_fmac_f32_e32 v31, v17, v16
	v_mul_f32_e32 v16, 0xbfb8aa3b, v18
	v_exp_f32_e32 v16, v16
	v_mul_f32_e32 v17, 0xbfb8aa3b, v19
	v_exp_f32_e32 v17, v17
	v_lshlrev_b32_e32 v32, 16, v67
	v_add_f32_e32 v16, 1.0, v16
	v_rcp_f32_e32 v16, v16
	v_add_f32_e32 v17, 1.0, v17
	v_rcp_f32_e32 v17, v17
	v_lshlrev_b32_e32 v18, 16, v71
	v_fmac_f32_e32 v32, v16, v18
	v_and_b32_e32 v34, 0xffff0000, v67
	v_and_b32_e32 v16, 0xffff0000, v71
	v_fmac_f32_e32 v34, v17, v16
	v_cvt_pk_bf16_f32 v16, v33, v35
	v_cvt_pk_bf16_f32 v17, v30, v28
	v_cvt_pk_bf16_f32 v18, v29, v24
	v_cvt_pk_bf16_f32 v19, v26, v25
	global_store_dwordx4 v[102:103], v[16:19], off
	v_lshlrev_b32_e32 v24, 16, v16
	s_nop 0
	v_and_b32_e32 v16, 0xffff0000, v16
	v_mul_f32_e32 v16, v16, v16
	v_fmac_f32_e32 v16, v24, v24
	v_lshlrev_b32_e32 v24, 16, v17
	v_and_b32_e32 v17, 0xffff0000, v17
	v_mul_f32_e32 v17, v17, v17
	v_fmac_f32_e32 v17, v24, v24
	v_add_f32_e32 v16, v16, v17
	v_lshlrev_b32_e32 v17, 16, v18
	v_and_b32_e32 v18, 0xffff0000, v18
	v_mul_f32_e32 v18, v18, v18
	v_fmac_f32_e32 v18, v17, v17
	v_add_f32_e32 v16, v16, v18
	v_and_b32_e32 v18, 0xffff0000, v19
	v_lshlrev_b32_e32 v17, 16, v19
	v_mul_f32_e32 v18, v18, v18
	v_fmac_f32_e32 v18, v17, v17
	v_add_f32_e32 v16, v16, v18
	v_cvt_pk_bf16_f32 v18, v27, v20
	v_cvt_pk_bf16_f32 v19, v22, v21
	v_cvt_pk_bf16_f32 v20, v23, v31
	v_cvt_pk_bf16_f32 v21, v32, v34
	global_store_dwordx4 v[100:101], v[18:21], off
	v_and_b32_e32 v22, 0xffff0000, v18
	v_lshlrev_b32_e32 v17, 16, v18
	v_mul_f32_e32 v22, v22, v22
	v_fmac_f32_e32 v22, v17, v17
	v_add_f32_e32 v16, v16, v22
	v_and_b32_e32 v22, 0xffff0000, v19
	v_lshlrev_b32_e32 v17, 16, v19
	v_mul_f32_e32 v22, v22, v22
	v_fmac_f32_e32 v22, v17, v17
	v_add_f32_e32 v16, v16, v22
	v_and_b32_e32 v22, 0xffff0000, v20
	v_lshlrev_b32_e32 v17, 16, v20
	v_mul_f32_e32 v22, v22, v22
	v_fmac_f32_e32 v22, v17, v17
	v_add_f32_e32 v16, v16, v22
	v_and_b32_e32 v22, 0xffff0000, v21
	v_lshlrev_b32_e32 v17, 16, v21
	v_mul_f32_e32 v22, v22, v22
	v_fmac_f32_e32 v22, v17, v17
	v_add_f32_e32 v16, v16, v22
	v_mov_b32_e32 v17, v16
	s_nop 1
	v_permlane16_swap_b32_e32 v17, v16
	s_nop 1
	s_waitcnt lgkmcnt(0)
	v_add_f32_e32 v16, v16, v17
	v_mov_b32_e32 v17, v16
	s_nop 1
	v_permlane32_swap_b32_e32 v17, v16
	s_nop 1
	s_and_saveexec_b64 s[12:13], vcc
	s_cbranch_execz .LBB0_252
	s_waitcnt lgkmcnt(0)
	v_add_f32_e32 v16, v16, v17
	v_mul_f32_e32 v16, 0x49800000, v16
	v_trunc_f32_e32 v16, v16
	v_mul_f32_e32 v17, 0x2f800000, v16
	v_floor_f32_e32 v17, v17
	v_fmac_f32_e32 v16, 0xcf800000, v17
	v_cvt_u32_f32_e32 v16, v16
	v_cvt_u32_f32_e32 v17, v17
	global_atomic_add_x2 v[192:193], v[16:17], off offset:1280
; #define EP_LOAD(q) do { _Pragma("unroll") for (int bj = 0; bj < 2; ++bj) { const unsigned o = ER_OFF(q, bj); t[(q) & 1][bj] = *(const u32x4*)(base + o); pw[(q) & 1][bj] = *(const u32x4*)(pp + o); } } while (0)
;     __device__ __forceinline__ void operator()(f32x4 (&acc)[2][2][4][2], const Unit& u, int wr, int wc, int fr, int fq) const {
;     ...
;         bf16_t* hb = pp;
;         EP_LOAD(0); EP_LOAD(1); EP_ADD(0); EP_ADD(1);
; #pragma unroll
;         for (int q = 0; q < 8; q += 2) { if (q < 6) { EP_LOAD(q + 2); EP_LOAD(q + 3); } ER_STORE(q); ER_STORE(q + 1); if (q < 6) { EP_ADD(q + 2); EP_ADD(q + 3); } }
.LBB0_252:
	s_or_b64 exec, exec, s[12:13]
	v_ffbh_u32_e32 v16, v167
	v_min_u32_e32 v18, 32, v16
	s_waitcnt lgkmcnt(0)
	v_lshlrev_b64 v[16:17], v18, v[166:167]
	v_min_u32_e32 v16, 1, v16
	v_or_b32_e32 v16, v17, v16
	v_cvt_f32_u32_e32 v16, v16
	v_sub_u32_e32 v17, 32, v18
	v_lshlrev_b32_e32 v18, 16, v60
	s_waitcnt vmcnt(8)
	v_and_b32_e32 v19, 0xffff0000, v56
	v_ldexp_f32 v16, v16, v17
	v_fmamk_f32 v16, v16, 0x30800000, v223
	v_rsq_f32_e32 v16, v16
	v_lshlrev_b32_e32 v17, 16, v56
	v_and_b32_e32 v22, 0xffff0000, v60
	v_pk_mul_f32 v[12:13], v[12:13], v[16:17] op_sel_hi:[1,0]
	s_nop 0
	v_mul_f32_e32 v12, 0xbfb8aa3b, v12
	v_mul_f32_e32 v13, 0xbfb8aa3b, v13
	v_exp_f32_e32 v20, v12
	v_exp_f32_e32 v21, v13
	v_pk_mul_f32 v[12:13], v[14:15], v[16:17] op_sel_hi:[1,0]
	v_pk_mul_f32 v[8:9], v[8:9], v[16:17] op_sel_hi:[1,0]
	v_mul_f32_e32 v12, 0xbfb8aa3b, v12
	v_exp_f32_e32 v12, v12
	v_mul_f32_e32 v13, 0xbfb8aa3b, v13
	v_exp_f32_e32 v13, v13
	v_mul_f32_e32 v8, 0xbfb8aa3b, v8
	v_exp_f32_e32 v8, v8
	v_mul_f32_e32 v9, 0xbfb8aa3b, v9
	v_add_f32_e32 v14, 1.0, v20
	v_add_f32_e32 v15, 1.0, v21
	v_exp_f32_e32 v9, v9
	v_rcp_f32_e32 v14, v14
	v_rcp_f32_e32 v15, v15
	v_add_f32_e32 v12, 1.0, v12
	v_rcp_f32_e32 v12, v12
	v_add_f32_e32 v13, 1.0, v13
	v_rcp_f32_e32 v13, v13
	v_add_f32_e32 v8, 1.0, v8
	v_rcp_f32_e32 v8, v8
	v_add_f32_e32 v9, 1.0, v9
	v_pk_mul_f32 v[10:11], v[10:11], v[16:17] op_sel_hi:[1,0]
	v_fmac_f32_e32 v17, v14, v18
	v_fmac_f32_e32 v19, v15, v22
	v_lshlrev_b32_e32 v14, 16, v57
	v_lshlrev_b32_e32 v15, 16, v61
	v_rcp_f32_e32 v9, v9
	v_fmac_f32_e32 v14, v12, v15
	v_and_b32_e32 v12, 0xffff0000, v57
	v_and_b32_e32 v15, 0xffff0000, v61
	v_fmac_f32_e32 v12, v13, v15
	v_lshlrev_b32_e32 v13, 16, v58
	v_lshlrev_b32_e32 v15, 16, v62
	v_fmac_f32_e32 v13, v8, v15
	v_and_b32_e32 v8, 0xffff0000, v58
	v_and_b32_e32 v15, 0xffff0000, v62
	v_fmac_f32_e32 v8, v9, v15
	v_mul_f32_e32 v9, 0xbfb8aa3b, v10
	v_exp_f32_e32 v9, v9
	v_mul_f32_e32 v11, 0xbfb8aa3b, v11
	v_pk_mul_f32 v[4:5], v[4:5], v[16:17] op_sel_hi:[1,0]
	v_exp_f32_e32 v11, v11
	v_mul_f32_e32 v4, 0xbfb8aa3b, v4
	v_exp_f32_e32 v4, v4
	v_mul_f32_e32 v5, 0xbfb8aa3b, v5
	v_exp_f32_e32 v5, v5
	v_add_f32_e32 v9, 1.0, v9
	v_rcp_f32_e32 v9, v9
	v_add_f32_e32 v11, 1.0, v11
	v_rcp_f32_e32 v11, v11
	v_add_f32_e32 v4, 1.0, v4
	v_rcp_f32_e32 v4, v4
	v_add_f32_e32 v5, 1.0, v5
	v_lshlrev_b32_e32 v10, 16, v59
	v_lshlrev_b32_e32 v15, 16, v63
	v_rcp_f32_e32 v5, v5
	v_fmac_f32_e32 v10, v9, v15
	v_and_b32_e32 v9, 0xffff0000, v59
	v_and_b32_e32 v15, 0xffff0000, v63
	v_fmac_f32_e32 v9, v11, v15
	s_waitcnt vmcnt(6)
	v_lshlrev_b32_e32 v11, 16, v48
	v_lshlrev_b32_e32 v15, 16, v52
	v_pk_mul_f32 v[6:7], v[6:7], v[16:17] op_sel_hi:[1,0]
	v_fmac_f32_e32 v11, v4, v15
	v_and_b32_e32 v4, 0xffff0000, v48
	v_and_b32_e32 v15, 0xffff0000, v52
	v_fmac_f32_e32 v4, v5, v15
	v_mul_f32_e32 v5, 0xbfb8aa3b, v6
	v_pk_mul_f32 v[0:1], v[0:1], v[16:17] op_sel_hi:[1,0]
	v_exp_f32_e32 v5, v5
	v_mul_f32_e32 v7, 0xbfb8aa3b, v7
	v_exp_f32_e32 v7, v7
	v_mul_f32_e32 v0, 0xbfb8aa3b, v0
	v_exp_f32_e32 v0, v0
	v_mul_f32_e32 v1, 0xbfb8aa3b, v1
	v_exp_f32_e32 v1, v1
	v_add_f32_e32 v5, 1.0, v5
	v_rcp_f32_e32 v5, v5
	v_add_f32_e32 v7, 1.0, v7
	v_rcp_f32_e32 v7, v7
	v_add_f32_e32 v0, 1.0, v0
	v_rcp_f32_e32 v0, v0
	v_add_f32_e32 v1, 1.0, v1
	v_lshlrev_b32_e32 v6, 16, v49
	v_lshlrev_b32_e32 v15, 16, v53
	v_rcp_f32_e32 v1, v1
	v_fmac_f32_e32 v6, v5, v15
	v_and_b32_e32 v5, 0xffff0000, v49
	v_and_b32_e32 v15, 0xffff0000, v53
	v_fmac_f32_e32 v5, v7, v15
	v_lshlrev_b32_e32 v7, 16, v50
	v_lshlrev_b32_e32 v15, 16, v54
	v_pk_mul_f32 v[2:3], v[2:3], v[16:17] op_sel_hi:[1,0]
	v_fmac_f32_e32 v7, v0, v15
	v_and_b32_e32 v15, 0xffff0000, v50
	v_and_b32_e32 v0, 0xffff0000, v54
	v_fmac_f32_e32 v15, v1, v0
	v_mul_f32_e32 v0, 0xbfb8aa3b, v2
	v_exp_f32_e32 v0, v0
	v_mul_f32_e32 v1, 0xbfb8aa3b, v3
	v_exp_f32_e32 v1, v1
	v_lshlrev_b32_e32 v16, 16, v51
	v_add_f32_e32 v0, 1.0, v0
	v_rcp_f32_e32 v0, v0
	v_add_f32_e32 v1, 1.0, v1
	v_rcp_f32_e32 v1, v1
	v_lshlrev_b32_e32 v2, 16, v55
	v_fmac_f32_e32 v16, v0, v2
	v_and_b32_e32 v18, 0xffff0000, v51
	v_and_b32_e32 v0, 0xffff0000, v55
	v_fmac_f32_e32 v18, v1, v0
	v_cvt_pk_bf16_f32 v0, v17, v19
	v_cvt_pk_bf16_f32 v1, v14, v12
	v_cvt_pk_bf16_f32 v2, v13, v8
	v_cvt_pk_bf16_f32 v3, v10, v9
	global_store_dwordx4 v[98:99], v[0:3], off
	v_lshlrev_b32_e32 v8, 16, v0
	s_nop 0
	v_and_b32_e32 v0, 0xffff0000, v0
	v_mul_f32_e32 v0, v0, v0
	v_fmac_f32_e32 v0, v8, v8
	v_lshlrev_b32_e32 v8, 16, v1
	v_and_b32_e32 v1, 0xffff0000, v1
	v_mul_f32_e32 v1, v1, v1
	v_fmac_f32_e32 v1, v8, v8
	v_add_f32_e32 v0, v0, v1
	v_lshlrev_b32_e32 v1, 16, v2
	v_and_b32_e32 v2, 0xffff0000, v2
	v_mul_f32_e32 v2, v2, v2
	v_fmac_f32_e32 v2, v1, v1
	v_add_f32_e32 v0, v0, v2
	v_and_b32_e32 v2, 0xffff0000, v3
	v_lshlrev_b32_e32 v1, 16, v3
	v_mul_f32_e32 v2, v2, v2
	v_fmac_f32_e32 v2, v1, v1
	v_add_f32_e32 v0, v0, v2
	v_cvt_pk_bf16_f32 v2, v11, v4
	v_cvt_pk_bf16_f32 v3, v6, v5
	v_cvt_pk_bf16_f32 v4, v7, v15
	v_cvt_pk_bf16_f32 v5, v16, v18
	global_store_dwordx4 v[96:97], v[2:5], off
	v_and_b32_e32 v6, 0xffff0000, v2
	v_lshlrev_b32_e32 v1, 16, v2
	v_mul_f32_e32 v6, v6, v6
	v_fmac_f32_e32 v6, v1, v1
	v_add_f32_e32 v0, v0, v6
	v_and_b32_e32 v6, 0xffff0000, v3
	v_lshlrev_b32_e32 v1, 16, v3
	v_mul_f32_e32 v6, v6, v6
	v_fmac_f32_e32 v6, v1, v1
	v_add_f32_e32 v0, v0, v6
	v_and_b32_e32 v6, 0xffff0000, v4
	v_lshlrev_b32_e32 v1, 16, v4
	v_mul_f32_e32 v6, v6, v6
	v_fmac_f32_e32 v6, v1, v1
	v_add_f32_e32 v0, v0, v6
	v_and_b32_e32 v6, 0xffff0000, v5
	v_lshlrev_b32_e32 v1, 16, v5
	v_mul_f32_e32 v6, v6, v6
	v_fmac_f32_e32 v6, v1, v1
	v_add_f32_e32 v0, v0, v6
	v_mov_b32_e32 v1, v0
	s_nop 1
	v_permlane16_swap_b32_e32 v1, v0
	s_nop 1
	s_waitcnt lgkmcnt(0)
	v_add_f32_e32 v0, v0, v1
	v_mov_b32_e32 v1, v0
	s_nop 1
	v_permlane32_swap_b32_e32 v1, v0
	s_nop 1
	s_and_saveexec_b64 s[12:13], vcc
	s_cbranch_execz .LBB0_227
	s_waitcnt lgkmcnt(0)
	v_add_f32_e32 v0, v0, v1
	v_mul_f32_e32 v0, 0x49800000, v0
	v_trunc_f32_e32 v0, v0
	v_mul_f32_e32 v1, 0x2f800000, v0
	v_floor_f32_e32 v1, v1
	v_fmac_f32_e32 v0, 0xcf800000, v1
	v_cvt_u32_f32_e32 v0, v0
	v_cvt_u32_f32_e32 v1, v1
	global_atomic_add_x2 v[192:193], v[0:1], off offset:1408
	s_branch .LBB0_227

; #define ER_LOAD(q) do { _Pragma("unroll") for (int bj = 0; bj < 2; ++bj) t[(q) & 3][bj] = *(const u32x4*)(base + ER_OFF(q, bj)); } while (0)
; #define ER_ADD(q) do { _Pragma("unroll") for (int bj = 0; bj < 2; ++bj) { f32x4& a0 = acc[(q) >> 2][bj][(q) & 3][0]; f32x4& a1 = acc[(q) >> 2][bj][(q) & 3][1]; const u32x4 p = t[(q) & 3][bj]; \
;             a0[0] += bf_lo(p.x); a0[1] += bf_hi(p.x); a0[2] += bf_lo(p.y); a0[3] += bf_hi(p.y); a1[0] += bf_lo(p.z); a1[1] += bf_hi(p.z); a1[2] += bf_lo(p.w); a1[3] += bf_hi(p.w); } } while (0)
;     __device__ __forceinline__ void operator()(f32x4 (&acc)[2][2][4][2], const Unit& u, int wr, int wc, int fr, int fq) const {
;         const int row0 = u.pm * BM + wr * 64 + fr, col0 = u.pn * BM + wc * 32 + 8 * fq; const unsigned off0 = (unsigned)row0 * 1024u + (unsigned)col0;
;         u32x4 t[4][2];
;     ...
; #pragma unroll
;         for (int q = 0; q < 4; ++q) ER_LOAD(q);
; #pragma unroll
;         for (int q = 0; q < 4; ++q) ER_ADD(q);
; #pragma unroll
;         for (int q = 4; q < 8; ++q) ER_LOAD(q);
; #pragma unroll
;         for (int q = 0; q < 4; ++q) ER_STORE(q);
; #pragma unroll
;         for (int q = 4; q < 8; ++q) { ER_ADD(q); ER_STORE(q); }
.LBB0_276:
	v_mov_b32_e32 v128, v170
	s_lshl_b32 s11, s67, 8
	v_readfirstlane_b32 s10, v128
	s_ashr_i32 s14, s10, 2
	s_andn2_b32 s14, s14, 63
	s_lshr_b32 s10, s10, 1
	s_add_i32 s14, s14, s11
	s_lshl_b32 s11, s66, 8
	s_and_b32 s10, s10, 0x60
	v_bfe_u32 v173, v128, 4, 2
	s_or_b32 s10, s10, s11
	v_and_or_b32 v218, v128, 15, s14
	v_lshl_or_b32 v128, v173, 3, s10
	v_lshl_add_u32 v140, v218, 10, v128
	v_mov_b32_e32 v141, v169
	v_lshlrev_b64 v[220:221], 1, v[140:141]
	v_lshl_add_u64 v[132:133], v[176:177], 0, v[220:221]
	global_load_dwordx4 v[128:131], v[132:133], off
	global_load_dwordx4 v[142:145], v[132:133], off offset:256
	v_add_u32_e32 v168, 0x4000, v140
	v_add_u32_e32 v202, 0x20000, v140
	v_mov_b32_e32 v203, v169
	v_lshl_add_u64 v[132:133], v[168:169], 1, v[176:177]
	v_add_u32_e32 v216, 0x4080, v140
	v_mov_b32_e32 v217, v169
	v_add_u32_e32 v210, 0x20080, v140
	v_mov_b32_e32 v211, v169
	global_load_dwordx4 v[160:163], v[132:133], off
	v_add_u32_e32 v214, 0x8000, v140
	v_mov_b32_e32 v215, v169
	v_add_u32_e32 v206, 0x24000, v140
	v_mov_b32_e32 v207, v169
	v_add_u32_e32 v212, 0x8080, v140
	v_mov_b32_e32 v213, v169
	v_add_u32_e32 v200, 0x24080, v140
	v_mov_b32_e32 v201, v169
	v_add_u32_e32 v208, 0xc000, v140
	v_mov_b32_e32 v209, v169
	v_add_u32_e32 v198, 0x28000, v140
	v_mov_b32_e32 v199, v169
	v_add_u32_e32 v204, 0xc080, v140
	v_mov_b32_e32 v205, v169
	v_add_u32_e32 v196, 0x28080, v140
	v_mov_b32_e32 v197, v169
	v_lshl_add_u64 v[136:137], v[204:205], 1, v[176:177]
	v_add_u32_e32 v194, 0x2c000, v140
	v_mov_b32_e32 v195, v169
	v_add_u32_e32 v192, 0x2c080, v140
	v_mov_b32_e32 v193, v169
	global_load_dwordx4 v[136:139], v[136:137], off
	v_cmp_eq_u32_e32 vcc, 0, v173
	v_lshl_add_u64 v[220:221], s[42:43], 0, v[220:221]
	v_cmp_lt_i32_e64 s[10:11], v233, v228
	v_ashrrev_i32_e32 v219, 31, v218
	v_lshl_add_u64 v[218:219], v[218:219], 3, s[40:41]
	s_waitcnt vmcnt(0)
	v_lshlrev_b32_e32 v141, 16, v128
	v_add_f32_e32 v248, v124, v141
	v_and_b32_e32 v124, 0xffff0000, v128
	v_add_f32_e32 v249, v125, v124
	v_lshlrev_b32_e32 v124, 16, v129
	v_add_f32_e32 v250, v126, v124
	v_and_b32_e32 v124, 0xffff0000, v129
	v_add_f32_e32 v251, v127, v124
	v_lshlrev_b32_e32 v124, 16, v130
	v_add_f32_e32 v252, v120, v124
	v_and_b32_e32 v120, 0xffff0000, v130
	v_add_f32_e32 v253, v121, v120
	v_lshlrev_b32_e32 v120, 16, v131
	v_add_f32_e32 v254, v122, v120
	v_and_b32_e32 v120, 0xffff0000, v131
	v_add_f32_e32 v237, v123, v120
	v_lshlrev_b32_e32 v120, 16, v142
	v_add_f32_e32 v240, v116, v120
	v_and_b32_e32 v116, 0xffff0000, v142
	v_add_f32_e32 v241, v117, v116
	v_lshlrev_b32_e32 v116, 16, v143
	v_add_f32_e32 v242, v118, v116
	v_and_b32_e32 v116, 0xffff0000, v143
	v_add_f32_e32 v243, v119, v116
	v_lshlrev_b32_e32 v116, 16, v144
	v_add_f32_e32 v244, v112, v116
	v_and_b32_e32 v112, 0xffff0000, v144
	v_add_f32_e32 v245, v113, v112
	v_lshlrev_b32_e32 v112, 16, v145
	v_add_f32_e32 v246, v114, v112
	v_and_b32_e32 v112, 0xffff0000, v145
	v_add_f32_e32 v247, v115, v112
	v_lshl_add_u64 v[112:113], v[202:203], 1, v[176:177]
	global_load_dwordx4 v[144:147], v[112:113], off
	v_lshl_add_u64 v[132:133], v[216:217], 1, v[176:177]
	v_lshl_add_u64 v[112:113], v[210:211], 1, v[176:177]
	global_load_dwordx4 v[164:167], v[132:133], off
	global_load_dwordx4 v[148:151], v[112:113], off
	v_lshl_add_u64 v[132:133], v[214:215], 1, v[176:177]
	v_lshl_add_u64 v[112:113], v[206:207], 1, v[176:177]
	global_load_dwordx4 v[152:155], v[132:133], off
	global_load_dwordx4 v[124:127], v[112:113], off
	v_lshl_add_u64 v[132:133], v[212:213], 1, v[176:177]
	v_lshl_add_u64 v[112:113], v[200:201], 1, v[176:177]
	global_load_dwordx4 v[156:159], v[132:133], off
	global_load_dwordx4 v[128:131], v[112:113], off
	v_lshl_add_u64 v[132:133], v[208:209], 1, v[176:177]
	v_lshl_add_u64 v[112:113], v[198:199], 1, v[176:177]
	global_load_dwordx4 v[132:135], v[132:133], off
	v_lshl_add_u64 v[140:141], v[192:193], 1, v[176:177]
	global_load_dwordx4 v[116:119], v[112:113], off
	v_lshl_add_u64 v[112:113], v[196:197], 1, v[176:177]
	global_load_dwordx4 v[120:123], v[112:113], off
	v_lshl_add_u64 v[112:113], v[194:195], 1, v[176:177]
	global_load_dwordx4 v[112:115], v[112:113], off
	s_nop 0
	global_load_dwordx4 v[140:143], v[140:141], off
	v_cvt_pk_bf16_f32 v248, v248, v249
	v_cvt_pk_bf16_f32 v249, v250, v251
	v_cvt_pk_bf16_f32 v250, v252, v253
	v_cvt_pk_bf16_f32 v251, v254, v237
	global_store_dwordx4 v[220:221], v[248:251], off
	v_and_b32_e32 v226, 0xffff0000, v248
	v_lshlrev_b32_e32 v173, 16, v248
	v_mul_f32_e32 v226, v226, v226
	v_and_b32_e32 v227, 0xffff0000, v249
	v_fmac_f32_e32 v226, v173, v173
	v_lshlrev_b32_e32 v173, 16, v249
	v_mul_f32_e32 v227, v227, v227
	v_fmac_f32_e32 v227, v173, v173
	v_add_f32_e32 v173, v226, v227
	v_and_b32_e32 v227, 0xffff0000, v250
	v_lshlrev_b32_e32 v226, 16, v250
	v_mul_f32_e32 v227, v227, v227
	v_fmac_f32_e32 v227, v226, v226
	v_add_f32_e32 v173, v173, v227
	v_and_b32_e32 v227, 0xffff0000, v251
	v_lshlrev_b32_e32 v226, 16, v251
	v_mul_f32_e32 v227, v227, v227
	v_cvt_pk_bf16_f32 v240, v240, v241
	v_cvt_pk_bf16_f32 v241, v242, v243
	v_cvt_pk_bf16_f32 v242, v244, v245
	v_cvt_pk_bf16_f32 v243, v246, v247
	global_store_dwordx4 v[220:221], v[240:243], off offset:256
	v_and_b32_e32 v221, 0xffff0000, v240
	v_fmac_f32_e32 v227, v226, v226
	v_lshlrev_b32_e32 v220, 16, v240
	v_mul_f32_e32 v221, v221, v221
	v_add_f32_e32 v173, v173, v227
	v_fmac_f32_e32 v221, v220, v220
	v_add_f32_e32 v173, v173, v221
	v_and_b32_e32 v221, 0xffff0000, v241
	v_lshlrev_b32_e32 v220, 16, v241
	v_mul_f32_e32 v221, v221, v221
	v_fmac_f32_e32 v221, v220, v220
	v_add_f32_e32 v173, v173, v221
	v_and_b32_e32 v221, 0xffff0000, v242
	v_lshlrev_b32_e32 v220, 16, v242
	v_mul_f32_e32 v221, v221, v221
	v_fmac_f32_e32 v221, v220, v220
	v_add_f32_e32 v173, v173, v221
	v_and_b32_e32 v221, 0xffff0000, v243
	v_lshlrev_b32_e32 v220, 16, v243
	v_mul_f32_e32 v221, v221, v221
	v_fmac_f32_e32 v221, v220, v220
	v_add_f32_e32 v220, v173, v221
	v_cndmask_b32_e64 v173, v225, v233, s[10:11]
	v_lshlrev_b32_e32 v173, 2, v173
	v_mov_b32_e32 v221, v220
	s_nop 1
	v_permlane16_swap_b32_e32 v221, v220
	s_nop 1
	v_cmp_lt_i32_e64 s[10:11], v234, v228
	s_waitcnt lgkmcnt(0)
	v_add_f32_e32 v221, v220, v221
	v_cndmask_b32_e64 v220, v225, v234, s[10:11]
	v_lshlrev_b32_e32 v220, 2, v220
	v_mov_b32_e32 v237, v221
	s_nop 1
	v_permlane32_swap_b32_e32 v237, v221
	s_nop 1
	s_and_saveexec_b64 s[10:11], vcc
	s_cbranch_execz .LBB0_278
	s_waitcnt lgkmcnt(0)
	v_add_f32_e32 v221, v221, v237
	v_mul_f32_e32 v221, 0x49800000, v221
	v_trunc_f32_e32 v221, v221
	v_mul_f32_e32 v226, 0x2f800000, v221
	v_floor_f32_e32 v227, v226
	v_fmac_f32_e32 v221, 0xcf800000, v227
	v_cvt_u32_f32_e32 v226, v221
	v_cvt_u32_f32_e32 v227, v227
	global_atomic_add_x2 v[218:219], v[226:227], off
; #define ER_LOAD(q) do { _Pragma("unroll") for (int bj = 0; bj < 2; ++bj) t[(q) & 3][bj] = *(const u32x4*)(base + ER_OFF(q, bj)); } while (0)
; #define ER_ADD(q) do { _Pragma("unroll") for (int bj = 0; bj < 2; ++bj) { f32x4& a0 = acc[(q) >> 2][bj][(q) & 3][0]; f32x4& a1 = acc[(q) >> 2][bj][(q) & 3][1]; const u32x4 p = t[(q) & 3][bj]; \
;             a0[0] += bf_lo(p.x); a0[1] += bf_hi(p.x); a0[2] += bf_lo(p.y); a0[3] += bf_hi(p.y); a1[0] += bf_lo(p.z); a1[1] += bf_hi(p.z); a1[2] += bf_lo(p.w); a1[3] += bf_hi(p.w); } } while (0)
;     __device__ __forceinline__ void operator()(f32x4 (&acc)[2][2][4][2], const Unit& u, int wr, int wc, int fr, int fq) const {
;         const int row0 = u.pm * BM + wr * 64 + fr, col0 = u.pn * BM + wc * 32 + 8 * fq; const unsigned off0 = (unsigned)row0 * 1024u + (unsigned)col0;
;         u32x4 t[4][2];
;     ...
; #pragma unroll
;         for (int q = 0; q < 4; ++q) ER_LOAD(q);
; #pragma unroll
;         for (int q = 0; q < 4; ++q) ER_ADD(q);
; #pragma unroll
;         for (int q = 4; q < 8; ++q) ER_LOAD(q);
; #pragma unroll
;         for (int q = 0; q < 4; ++q) ER_STORE(q);
; #pragma unroll
;         for (int q = 4; q < 8; ++q) { ER_ADD(q); ER_STORE(q); }
.LBB0_278:
	s_or_b64 exec, exec, s[10:11]
	v_lshlrev_b32_e32 v221, 16, v160
	v_and_b32_e32 v160, 0xffff0000, v160
	v_add_f32_e32 v109, v109, v160
	v_lshlrev_b32_e32 v160, 16, v161
	v_add_f32_e32 v110, v110, v160
	v_and_b32_e32 v160, 0xffff0000, v161
	v_add_f32_e32 v111, v111, v160
	v_lshlrev_b32_e32 v160, 16, v162
	v_add_f32_e32 v104, v104, v160
	v_and_b32_e32 v160, 0xffff0000, v162
	v_add_f32_e32 v105, v105, v160
	v_lshlrev_b32_e32 v160, 16, v163
	v_add_f32_e32 v106, v106, v160
	v_and_b32_e32 v160, 0xffff0000, v163
	v_add_f32_e32 v107, v107, v160
	s_waitcnt vmcnt(12)
	v_lshlrev_b32_e32 v160, 16, v164
	v_add_f32_e32 v160, v100, v160
	v_and_b32_e32 v100, 0xffff0000, v164
	v_add_f32_e32 v161, v101, v100
	v_lshlrev_b32_e32 v100, 16, v165
	v_add_f32_e32 v102, v102, v100
	v_and_b32_e32 v100, 0xffff0000, v165
	v_add_f32_e32 v103, v103, v100
	v_lshlrev_b32_e32 v100, 16, v166
	v_add_f32_e32 v162, v96, v100
	v_and_b32_e32 v96, 0xffff0000, v166
	v_add_f32_e32 v163, v97, v96
	v_lshlrev_b32_e32 v96, 16, v167
	v_add_f32_e32 v164, v98, v96
	v_and_b32_e32 v96, 0xffff0000, v167
	v_add_f32_e32 v108, v108, v221
	v_add_f32_e32 v165, v99, v96
	v_cvt_pk_bf16_f32 v96, v108, v109
	v_lshl_add_u64 v[100:101], v[168:169], 1, s[42:43]
	v_cvt_pk_bf16_f32 v97, v110, v111
	v_cvt_pk_bf16_f32 v98, v104, v105
	v_cvt_pk_bf16_f32 v99, v106, v107
	global_store_dwordx4 v[100:101], v[96:99], off
	v_lshlrev_b32_e32 v100, 16, v96
	s_nop 0
	v_and_b32_e32 v96, 0xffff0000, v96
	v_mul_f32_e32 v96, v96, v96
	v_fmac_f32_e32 v96, v100, v100
	v_lshlrev_b32_e32 v100, 16, v97
	v_and_b32_e32 v97, 0xffff0000, v97
	v_mul_f32_e32 v97, v97, v97
	v_fmac_f32_e32 v97, v100, v100
	v_add_f32_e32 v96, v96, v97
	v_lshlrev_b32_e32 v97, 16, v98
	v_and_b32_e32 v98, 0xffff0000, v98
	v_mul_f32_e32 v98, v98, v98
	v_fmac_f32_e32 v98, v97, v97
	v_add_f32_e32 v96, v96, v98
	v_and_b32_e32 v98, 0xffff0000, v99
	v_lshlrev_b32_e32 v97, 16, v99
	v_mul_f32_e32 v98, v98, v98
	v_fmac_f32_e32 v98, v97, v97
	v_add_f32_e32 v96, v96, v98
	v_cvt_pk_bf16_f32 v98, v160, v161
	v_cvt_pk_bf16_f32 v99, v102, v103
	v_cvt_pk_bf16_f32 v100, v162, v163
	v_cvt_pk_bf16_f32 v101, v164, v165
	s_nop 0
	v_and_b32_e32 v102, 0xffff0000, v98
	v_lshlrev_b32_e32 v97, 16, v98
	v_mul_f32_e32 v102, v102, v102
	v_fmac_f32_e32 v102, v97, v97
	v_add_f32_e32 v96, v96, v102
	v_and_b32_e32 v102, 0xffff0000, v99
	v_lshlrev_b32_e32 v97, 16, v99
	v_mul_f32_e32 v102, v102, v102
	v_fmac_f32_e32 v102, v97, v97
	v_add_f32_e32 v96, v96, v102
	v_and_b32_e32 v102, 0xffff0000, v100
	v_lshlrev_b32_e32 v97, 16, v100
	v_mul_f32_e32 v102, v102, v102
	v_fmac_f32_e32 v102, v97, v97
	v_add_f32_e32 v96, v96, v102
	v_and_b32_e32 v102, 0xffff0000, v101
	v_lshlrev_b32_e32 v97, 16, v101
	v_mul_f32_e32 v102, v102, v102
	v_fmac_f32_e32 v102, v97, v97
	v_add_f32_e32 v96, v96, v102
	v_mov_b32_e32 v97, v96
	s_nop 1
	v_permlane16_swap_b32_e32 v97, v96
	s_nop 1
	v_lshl_add_u64 v[102:103], v[216:217], 1, s[42:43]
	global_store_dwordx4 v[102:103], v[98:101], off
	s_waitcnt lgkmcnt(0)
	v_add_f32_e32 v96, v96, v97
	v_mov_b32_e32 v97, v96
	s_nop 1
	v_permlane32_swap_b32_e32 v97, v96
	s_nop 1
	s_and_saveexec_b64 s[10:11], vcc
	s_cbranch_execz .LBB0_280
	s_waitcnt lgkmcnt(0)
	v_add_f32_e32 v96, v96, v97
	v_mul_f32_e32 v96, 0x49800000, v96
	v_trunc_f32_e32 v96, v96
	v_mul_f32_e32 v97, 0x2f800000, v96
	v_floor_f32_e32 v97, v97
	v_fmac_f32_e32 v96, 0xcf800000, v97
	v_cvt_u32_f32_e32 v96, v96
	v_cvt_u32_f32_e32 v97, v97
	global_atomic_add_x2 v[218:219], v[96:97], off offset:128
.LBB0_280:
	s_or_b64 exec, exec, s[10:11]
	s_waitcnt vmcnt(12)
	v_lshlrev_b32_e32 v96, 16, v152
	v_add_f32_e32 v92, v92, v96
	v_and_b32_e32 v96, 0xffff0000, v152
	v_add_f32_e32 v93, v93, v96
	v_lshlrev_b32_e32 v96, 16, v153
	v_add_f32_e32 v94, v94, v96
	v_and_b32_e32 v96, 0xffff0000, v153
	v_add_f32_e32 v95, v95, v96
	v_lshlrev_b32_e32 v96, 16, v154
	v_add_f32_e32 v88, v88, v96
	v_and_b32_e32 v96, 0xffff0000, v154
	v_add_f32_e32 v89, v89, v96
	v_lshlrev_b32_e32 v96, 16, v155
	v_add_f32_e32 v90, v90, v96
	v_and_b32_e32 v96, 0xffff0000, v155
	v_add_f32_e32 v91, v91, v96
	s_waitcnt vmcnt(10)
	v_lshlrev_b32_e32 v96, 16, v156
	v_add_f32_e32 v96, v84, v96
	v_and_b32_e32 v84, 0xffff0000, v156
	s_waitcnt lgkmcnt(0)
	v_add_f32_e32 v97, v85, v84
	v_lshlrev_b32_e32 v84, 16, v157
	v_add_f32_e32 v86, v86, v84
	v_and_b32_e32 v84, 0xffff0000, v157
	v_add_f32_e32 v87, v87, v84
	v_lshlrev_b32_e32 v84, 16, v158
	v_add_f32_e32 v98, v80, v84
	v_and_b32_e32 v80, 0xffff0000, v158
	v_add_f32_e32 v99, v81, v80
	v_lshlrev_b32_e32 v80, 16, v159
	v_add_f32_e32 v100, v82, v80
	v_and_b32_e32 v80, 0xffff0000, v159
	v_add_f32_e32 v101, v83, v80
	v_cvt_pk_bf16_f32 v80, v92, v93
	v_lshl_add_u64 v[84:85], v[214:215], 1, s[42:43]
	v_cvt_pk_bf16_f32 v81, v94, v95
	v_cvt_pk_bf16_f32 v82, v88, v89
	v_cvt_pk_bf16_f32 v83, v90, v91
	global_store_dwordx4 v[84:85], v[80:83], off
	v_lshlrev_b32_e32 v84, 16, v80
	s_nop 0
	v_and_b32_e32 v80, 0xffff0000, v80
	v_mul_f32_e32 v80, v80, v80
	v_fmac_f32_e32 v80, v84, v84
	v_lshlrev_b32_e32 v84, 16, v81
	v_and_b32_e32 v81, 0xffff0000, v81
	v_mul_f32_e32 v81, v81, v81
	v_fmac_f32_e32 v81, v84, v84
	v_add_f32_e32 v80, v80, v81
	v_lshlrev_b32_e32 v81, 16, v82
	v_and_b32_e32 v82, 0xffff0000, v82
	v_mul_f32_e32 v82, v82, v82
	v_fmac_f32_e32 v82, v81, v81
	v_add_f32_e32 v80, v80, v82
	v_and_b32_e32 v82, 0xffff0000, v83
	v_lshlrev_b32_e32 v81, 16, v83
	v_mul_f32_e32 v82, v82, v82
	v_fmac_f32_e32 v82, v81, v81
	v_add_f32_e32 v80, v80, v82
	v_cvt_pk_bf16_f32 v82, v96, v97
	v_cvt_pk_bf16_f32 v83, v86, v87
	v_cvt_pk_bf16_f32 v84, v98, v99
	v_cvt_pk_bf16_f32 v85, v100, v101
	s_nop 0
	v_and_b32_e32 v86, 0xffff0000, v82
	v_lshlrev_b32_e32 v81, 16, v82
	v_mul_f32_e32 v86, v86, v86
	v_fmac_f32_e32 v86, v81, v81
	v_add_f32_e32 v80, v80, v86
	v_and_b32_e32 v86, 0xffff0000, v83
	v_lshlrev_b32_e32 v81, 16, v83
	v_mul_f32_e32 v86, v86, v86
	v_fmac_f32_e32 v86, v81, v81
	v_add_f32_e32 v80, v80, v86
	v_and_b32_e32 v86, 0xffff0000, v84
	v_lshlrev_b32_e32 v81, 16, v84
	v_mul_f32_e32 v86, v86, v86
	v_fmac_f32_e32 v86, v81, v81
	v_add_f32_e32 v80, v80, v86
	v_and_b32_e32 v86, 0xffff0000, v85
	v_lshlrev_b32_e32 v81, 16, v85
	v_mul_f32_e32 v86, v86, v86
	v_fmac_f32_e32 v86, v81, v81
	v_add_f32_e32 v80, v80, v86
	v_mov_b32_e32 v81, v80
	s_nop 1
	v_permlane16_swap_b32_e32 v81, v80
	s_nop 1
	v_lshl_add_u64 v[86:87], v[212:213], 1, s[42:43]
	global_store_dwordx4 v[86:87], v[82:85], off
	s_waitcnt lgkmcnt(0)
	v_add_f32_e32 v80, v80, v81
	v_mov_b32_e32 v81, v80
	s_nop 1
	v_permlane32_swap_b32_e32 v81, v80
	s_nop 1
	s_and_saveexec_b64 s[10:11], vcc
	s_cbranch_execz .LBB0_282
	s_waitcnt lgkmcnt(0)
	v_add_f32_e32 v80, v80, v81
	v_mul_f32_e32 v80, 0x49800000, v80
	v_trunc_f32_e32 v80, v80
	v_mul_f32_e32 v81, 0x2f800000, v80
	v_floor_f32_e32 v81, v81
	v_fmac_f32_e32 v80, 0xcf800000, v81
	v_cvt_u32_f32_e32 v80, v80
	v_cvt_u32_f32_e32 v81, v81
	global_atomic_add_x2 v[218:219], v[80:81], off offset:256
; #define ER_LOAD(q) do { _Pragma("unroll") for (int bj = 0; bj < 2; ++bj) t[(q) & 3][bj] = *(const u32x4*)(base + ER_OFF(q, bj)); } while (0)
; #define ER_ADD(q) do { _Pragma("unroll") for (int bj = 0; bj < 2; ++bj) { f32x4& a0 = acc[(q) >> 2][bj][(q) & 3][0]; f32x4& a1 = acc[(q) >> 2][bj][(q) & 3][1]; const u32x4 p = t[(q) & 3][bj]; \
;             a0[0] += bf_lo(p.x); a0[1] += bf_hi(p.x); a0[2] += bf_lo(p.y); a0[3] += bf_hi(p.y); a1[0] += bf_lo(p.z); a1[1] += bf_hi(p.z); a1[2] += bf_lo(p.w); a1[3] += bf_hi(p.w); } } while (0)
;     __device__ __forceinline__ void operator()(f32x4 (&acc)[2][2][4][2], const Unit& u, int wr, int wc, int fr, int fq) const {
;         const int row0 = u.pm * BM + wr * 64 + fr, col0 = u.pn * BM + wc * 32 + 8 * fq; const unsigned off0 = (unsigned)row0 * 1024u + (unsigned)col0;
;         u32x4 t[4][2];
;     ...
; #pragma unroll
;         for (int q = 0; q < 4; ++q) ER_LOAD(q);
; #pragma unroll
;         for (int q = 0; q < 4; ++q) ER_ADD(q);
; #pragma unroll
;         for (int q = 4; q < 8; ++q) ER_LOAD(q);
; #pragma unroll
;         for (int q = 0; q < 4; ++q) ER_STORE(q);
; #pragma unroll
;         for (int q = 4; q < 8; ++q) { ER_ADD(q); ER_STORE(q); }
.LBB0_282:
	s_or_b64 exec, exec, s[10:11]
	s_waitcnt vmcnt(10)
	v_lshlrev_b32_e32 v80, 16, v132
	v_add_f32_e32 v76, v76, v80
	v_and_b32_e32 v80, 0xffff0000, v132
	v_add_f32_e32 v77, v77, v80
	v_lshlrev_b32_e32 v80, 16, v133
	v_add_f32_e32 v78, v78, v80
	v_and_b32_e32 v80, 0xffff0000, v133
	v_add_f32_e32 v79, v79, v80
	v_lshlrev_b32_e32 v80, 16, v134
	v_add_f32_e32 v72, v72, v80
	v_and_b32_e32 v80, 0xffff0000, v134
	v_add_f32_e32 v73, v73, v80
	v_lshlrev_b32_e32 v80, 16, v135
	v_add_f32_e32 v74, v74, v80
	v_and_b32_e32 v80, 0xffff0000, v135
	v_add_f32_e32 v75, v75, v80
	v_lshlrev_b32_e32 v80, 16, v136
	v_add_f32_e32 v80, v68, v80
	v_and_b32_e32 v68, 0xffff0000, v136
	s_waitcnt lgkmcnt(0)
	v_add_f32_e32 v81, v69, v68
	v_lshlrev_b32_e32 v68, 16, v137
	v_add_f32_e32 v70, v70, v68
	v_and_b32_e32 v68, 0xffff0000, v137
	v_add_f32_e32 v71, v71, v68
	v_lshlrev_b32_e32 v68, 16, v138
	v_add_f32_e32 v82, v64, v68
	v_and_b32_e32 v64, 0xffff0000, v138
	v_add_f32_e32 v83, v65, v64
	v_lshlrev_b32_e32 v64, 16, v139
	v_add_f32_e32 v84, v66, v64
	v_and_b32_e32 v64, 0xffff0000, v139
	v_add_f32_e32 v85, v67, v64
	v_cvt_pk_bf16_f32 v64, v76, v77
	v_lshl_add_u64 v[68:69], v[208:209], 1, s[42:43]
	v_cvt_pk_bf16_f32 v65, v78, v79
	v_cvt_pk_bf16_f32 v66, v72, v73
	v_cvt_pk_bf16_f32 v67, v74, v75
	global_store_dwordx4 v[68:69], v[64:67], off
	v_lshlrev_b32_e32 v68, 16, v64
	s_nop 0
	v_and_b32_e32 v64, 0xffff0000, v64
	v_mul_f32_e32 v64, v64, v64
	v_fmac_f32_e32 v64, v68, v68
	v_lshlrev_b32_e32 v68, 16, v65
	v_and_b32_e32 v65, 0xffff0000, v65
	v_mul_f32_e32 v65, v65, v65
	v_fmac_f32_e32 v65, v68, v68
	v_add_f32_e32 v64, v64, v65
	v_lshlrev_b32_e32 v65, 16, v66
	v_and_b32_e32 v66, 0xffff0000, v66
	v_mul_f32_e32 v66, v66, v66
	v_fmac_f32_e32 v66, v65, v65
	v_add_f32_e32 v64, v64, v66
	v_and_b32_e32 v66, 0xffff0000, v67
	v_lshlrev_b32_e32 v65, 16, v67
	v_mul_f32_e32 v66, v66, v66
	v_fmac_f32_e32 v66, v65, v65
	v_add_f32_e32 v64, v64, v66
	v_cvt_pk_bf16_f32 v66, v80, v81
	v_cvt_pk_bf16_f32 v67, v70, v71
	v_cvt_pk_bf16_f32 v68, v82, v83
	v_cvt_pk_bf16_f32 v69, v84, v85
	s_nop 0
	v_and_b32_e32 v70, 0xffff0000, v66
	v_lshlrev_b32_e32 v65, 16, v66
	v_mul_f32_e32 v70, v70, v70
	v_fmac_f32_e32 v70, v65, v65
	v_add_f32_e32 v64, v64, v70
	v_and_b32_e32 v70, 0xffff0000, v67
	v_lshlrev_b32_e32 v65, 16, v67
	v_mul_f32_e32 v70, v70, v70
	v_fmac_f32_e32 v70, v65, v65
	v_add_f32_e32 v64, v64, v70
	v_and_b32_e32 v70, 0xffff0000, v68
	v_lshlrev_b32_e32 v65, 16, v68
	v_mul_f32_e32 v70, v70, v70
	v_fmac_f32_e32 v70, v65, v65
	v_add_f32_e32 v64, v64, v70
	v_and_b32_e32 v70, 0xffff0000, v69
	v_lshlrev_b32_e32 v65, 16, v69
	v_mul_f32_e32 v70, v70, v70
	v_fmac_f32_e32 v70, v65, v65
	v_add_f32_e32 v64, v64, v70
	v_mov_b32_e32 v65, v64
	s_nop 1
	v_permlane16_swap_b32_e32 v65, v64
	s_nop 1
	v_lshl_add_u64 v[70:71], v[204:205], 1, s[42:43]
	global_store_dwordx4 v[70:71], v[66:69], off
	s_waitcnt lgkmcnt(0)
	v_add_f32_e32 v64, v64, v65
	v_mov_b32_e32 v65, v64
	s_nop 1
	v_permlane32_swap_b32_e32 v65, v64
	s_nop 1
	s_and_saveexec_b64 s[10:11], vcc
	s_cbranch_execz .LBB0_284
	s_waitcnt lgkmcnt(0)
	v_add_f32_e32 v64, v64, v65
	v_mul_f32_e32 v64, 0x49800000, v64
	v_trunc_f32_e32 v64, v64
	v_mul_f32_e32 v65, 0x2f800000, v64
	v_floor_f32_e32 v65, v65
	v_fmac_f32_e32 v64, 0xcf800000, v65
	v_cvt_u32_f32_e32 v64, v64
	v_cvt_u32_f32_e32 v65, v65
	global_atomic_add_x2 v[218:219], v[64:65], off offset:384
.LBB0_284:
	s_or_b64 exec, exec, s[10:11]
	v_lshlrev_b32_e32 v64, 16, v144
	v_add_f32_e32 v60, v60, v64
	v_and_b32_e32 v64, 0xffff0000, v144
	v_add_f32_e32 v61, v61, v64
	v_lshlrev_b32_e32 v64, 16, v145
	v_add_f32_e32 v62, v62, v64
	v_and_b32_e32 v64, 0xffff0000, v145
	v_add_f32_e32 v63, v63, v64
	v_lshlrev_b32_e32 v64, 16, v146
	v_add_f32_e32 v56, v56, v64
	v_and_b32_e32 v64, 0xffff0000, v146
	v_add_f32_e32 v57, v57, v64
	v_lshlrev_b32_e32 v64, 16, v147
	v_add_f32_e32 v58, v58, v64
	v_and_b32_e32 v64, 0xffff0000, v147
	v_add_f32_e32 v59, v59, v64
	v_lshlrev_b32_e32 v64, 16, v148
	v_add_f32_e32 v64, v52, v64
	v_and_b32_e32 v52, 0xffff0000, v148
	s_waitcnt lgkmcnt(0)
	v_add_f32_e32 v65, v53, v52
	v_lshlrev_b32_e32 v52, 16, v149
	v_add_f32_e32 v54, v54, v52
	v_and_b32_e32 v52, 0xffff0000, v149
	v_add_f32_e32 v55, v55, v52
	v_lshlrev_b32_e32 v52, 16, v150
	v_add_f32_e32 v66, v48, v52
	v_and_b32_e32 v48, 0xffff0000, v150
	v_add_f32_e32 v67, v49, v48
	v_lshlrev_b32_e32 v48, 16, v151
	v_add_f32_e32 v68, v50, v48
	v_and_b32_e32 v48, 0xffff0000, v151
	v_add_f32_e32 v69, v51, v48
	v_cvt_pk_bf16_f32 v48, v60, v61
	v_lshl_add_u64 v[52:53], v[202:203], 1, s[42:43]
	v_cvt_pk_bf16_f32 v49, v62, v63
	v_cvt_pk_bf16_f32 v50, v56, v57
	v_cvt_pk_bf16_f32 v51, v58, v59
	global_store_dwordx4 v[52:53], v[48:51], off
	v_lshlrev_b32_e32 v52, 16, v48
	s_nop 0
	v_and_b32_e32 v48, 0xffff0000, v48
	v_mul_f32_e32 v48, v48, v48
	v_fmac_f32_e32 v48, v52, v52
	v_lshlrev_b32_e32 v52, 16, v49
	v_and_b32_e32 v49, 0xffff0000, v49
	v_mul_f32_e32 v49, v49, v49
	v_fmac_f32_e32 v49, v52, v52
	v_add_f32_e32 v48, v48, v49
	v_lshlrev_b32_e32 v49, 16, v50
	v_and_b32_e32 v50, 0xffff0000, v50
	v_mul_f32_e32 v50, v50, v50
	v_fmac_f32_e32 v50, v49, v49
	v_add_f32_e32 v48, v48, v50
	v_and_b32_e32 v50, 0xffff0000, v51
	v_lshlrev_b32_e32 v49, 16, v51
	v_mul_f32_e32 v50, v50, v50
	v_fmac_f32_e32 v50, v49, v49
	v_add_f32_e32 v48, v48, v50
	v_cvt_pk_bf16_f32 v50, v64, v65
	v_cvt_pk_bf16_f32 v51, v54, v55
	v_cvt_pk_bf16_f32 v52, v66, v67
	v_cvt_pk_bf16_f32 v53, v68, v69
	s_nop 0
	v_and_b32_e32 v54, 0xffff0000, v50
	v_lshlrev_b32_e32 v49, 16, v50
	v_mul_f32_e32 v54, v54, v54
	v_fmac_f32_e32 v54, v49, v49
	v_add_f32_e32 v48, v48, v54
	v_and_b32_e32 v54, 0xffff0000, v51
	v_lshlrev_b32_e32 v49, 16, v51
	v_mul_f32_e32 v54, v54, v54
	v_fmac_f32_e32 v54, v49, v49
	v_add_f32_e32 v48, v48, v54
	v_and_b32_e32 v54, 0xffff0000, v52
	v_lshlrev_b32_e32 v49, 16, v52
	v_mul_f32_e32 v54, v54, v54
	v_fmac_f32_e32 v54, v49, v49
	v_add_f32_e32 v48, v48, v54
	v_and_b32_e32 v54, 0xffff0000, v53
	v_lshlrev_b32_e32 v49, 16, v53
	v_mul_f32_e32 v54, v54, v54
	v_fmac_f32_e32 v54, v49, v49
	v_add_f32_e32 v48, v48, v54
	v_mov_b32_e32 v49, v48
	s_nop 1
	v_permlane16_swap_b32_e32 v49, v48
	s_nop 1
	v_lshl_add_u64 v[54:55], v[210:211], 1, s[42:43]
	global_store_dwordx4 v[54:55], v[50:53], off
	s_waitcnt lgkmcnt(0)
	v_add_f32_e32 v48, v48, v49
	v_mov_b32_e32 v49, v48
	s_nop 1
	v_permlane32_swap_b32_e32 v49, v48
	s_nop 1
	s_and_saveexec_b64 s[10:11], vcc
	s_cbranch_execz .LBB0_286
	s_waitcnt lgkmcnt(0)
	v_add_f32_e32 v48, v48, v49
	v_mul_f32_e32 v48, 0x49800000, v48
	v_trunc_f32_e32 v48, v48
	v_mul_f32_e32 v49, 0x2f800000, v48
	v_floor_f32_e32 v49, v49
	v_fmac_f32_e32 v48, 0xcf800000, v49
	v_cvt_u32_f32_e32 v48, v48
	v_cvt_u32_f32_e32 v49, v49
	global_atomic_add_x2 v[218:219], v[48:49], off offset:1024
; #define ER_LOAD(q) do { _Pragma("unroll") for (int bj = 0; bj < 2; ++bj) t[(q) & 3][bj] = *(const u32x4*)(base + ER_OFF(q, bj)); } while (0)
; #define ER_ADD(q) do { _Pragma("unroll") for (int bj = 0; bj < 2; ++bj) { f32x4& a0 = acc[(q) >> 2][bj][(q) & 3][0]; f32x4& a1 = acc[(q) >> 2][bj][(q) & 3][1]; const u32x4 p = t[(q) & 3][bj]; \
;             a0[0] += bf_lo(p.x); a0[1] += bf_hi(p.x); a0[2] += bf_lo(p.y); a0[3] += bf_hi(p.y); a1[0] += bf_lo(p.z); a1[1] += bf_hi(p.z); a1[2] += bf_lo(p.w); a1[3] += bf_hi(p.w); } } while (0)
;     __device__ __forceinline__ void operator()(f32x4 (&acc)[2][2][4][2], const Unit& u, int wr, int wc, int fr, int fq) const {
;         const int row0 = u.pm * BM + wr * 64 + fr, col0 = u.pn * BM + wc * 32 + 8 * fq; const unsigned off0 = (unsigned)row0 * 1024u + (unsigned)col0;
;         u32x4 t[4][2];
;     ...
; #pragma unroll
;         for (int q = 0; q < 4; ++q) ER_LOAD(q);
; #pragma unroll
;         for (int q = 0; q < 4; ++q) ER_ADD(q);
; #pragma unroll
;         for (int q = 4; q < 8; ++q) ER_LOAD(q);
; #pragma unroll
;         for (int q = 0; q < 4; ++q) ER_STORE(q);
; #pragma unroll
;         for (int q = 4; q < 8; ++q) { ER_ADD(q); ER_STORE(q); }
.LBB0_286:
	s_or_b64 exec, exec, s[10:11]
	v_lshlrev_b32_e32 v48, 16, v124
	v_add_f32_e32 v44, v44, v48
	v_and_b32_e32 v48, 0xffff0000, v124
	v_add_f32_e32 v45, v45, v48
	v_lshlrev_b32_e32 v48, 16, v125
	v_add_f32_e32 v46, v46, v48
	v_and_b32_e32 v48, 0xffff0000, v125
	v_add_f32_e32 v47, v47, v48
	v_lshlrev_b32_e32 v48, 16, v126
	v_add_f32_e32 v40, v40, v48
	v_and_b32_e32 v48, 0xffff0000, v126
	v_add_f32_e32 v41, v41, v48
	v_lshlrev_b32_e32 v48, 16, v127
	v_add_f32_e32 v42, v42, v48
	v_and_b32_e32 v48, 0xffff0000, v127
	v_add_f32_e32 v43, v43, v48
	v_lshlrev_b32_e32 v48, 16, v128
	v_add_f32_e32 v48, v36, v48
	v_and_b32_e32 v36, 0xffff0000, v128
	s_waitcnt lgkmcnt(0)
	v_add_f32_e32 v49, v37, v36
	v_lshlrev_b32_e32 v36, 16, v129
	v_add_f32_e32 v38, v38, v36
	v_and_b32_e32 v36, 0xffff0000, v129
	v_add_f32_e32 v39, v39, v36
	v_lshlrev_b32_e32 v36, 16, v130
	v_add_f32_e32 v50, v32, v36
	v_and_b32_e32 v32, 0xffff0000, v130
	v_add_f32_e32 v51, v33, v32
	v_lshlrev_b32_e32 v32, 16, v131
	v_add_f32_e32 v52, v34, v32
	v_and_b32_e32 v32, 0xffff0000, v131
	v_add_f32_e32 v53, v35, v32
	v_cvt_pk_bf16_f32 v32, v44, v45
	v_lshl_add_u64 v[36:37], v[206:207], 1, s[42:43]
	v_cvt_pk_bf16_f32 v33, v46, v47
	v_cvt_pk_bf16_f32 v34, v40, v41
	v_cvt_pk_bf16_f32 v35, v42, v43
	global_store_dwordx4 v[36:37], v[32:35], off
	v_lshlrev_b32_e32 v36, 16, v32
	s_nop 0
	v_and_b32_e32 v32, 0xffff0000, v32
	v_mul_f32_e32 v32, v32, v32
	v_fmac_f32_e32 v32, v36, v36
	v_lshlrev_b32_e32 v36, 16, v33
	v_and_b32_e32 v33, 0xffff0000, v33
	v_mul_f32_e32 v33, v33, v33
	v_fmac_f32_e32 v33, v36, v36
	v_add_f32_e32 v32, v32, v33
	v_lshlrev_b32_e32 v33, 16, v34
	v_and_b32_e32 v34, 0xffff0000, v34
	v_mul_f32_e32 v34, v34, v34
	v_fmac_f32_e32 v34, v33, v33
	v_add_f32_e32 v32, v32, v34
	v_and_b32_e32 v34, 0xffff0000, v35
	v_lshlrev_b32_e32 v33, 16, v35
	v_mul_f32_e32 v34, v34, v34
	v_fmac_f32_e32 v34, v33, v33
	v_add_f32_e32 v32, v32, v34
	v_cvt_pk_bf16_f32 v34, v48, v49
	v_cvt_pk_bf16_f32 v35, v38, v39
	v_cvt_pk_bf16_f32 v36, v50, v51
	v_cvt_pk_bf16_f32 v37, v52, v53
	s_nop 0
	v_and_b32_e32 v38, 0xffff0000, v34
	v_lshlrev_b32_e32 v33, 16, v34
	v_mul_f32_e32 v38, v38, v38
	v_fmac_f32_e32 v38, v33, v33
	v_add_f32_e32 v32, v32, v38
	v_and_b32_e32 v38, 0xffff0000, v35
	v_lshlrev_b32_e32 v33, 16, v35
	v_mul_f32_e32 v38, v38, v38
	v_fmac_f32_e32 v38, v33, v33
	v_add_f32_e32 v32, v32, v38
	v_and_b32_e32 v38, 0xffff0000, v36
	v_lshlrev_b32_e32 v33, 16, v36
	v_mul_f32_e32 v38, v38, v38
	v_fmac_f32_e32 v38, v33, v33
	v_add_f32_e32 v32, v32, v38
	v_and_b32_e32 v38, 0xffff0000, v37
	v_lshlrev_b32_e32 v33, 16, v37
	v_mul_f32_e32 v38, v38, v38
	v_fmac_f32_e32 v38, v33, v33
	v_add_f32_e32 v32, v32, v38
	v_mov_b32_e32 v33, v32
	s_nop 1
	v_permlane16_swap_b32_e32 v33, v32
	s_nop 1
	v_lshl_add_u64 v[38:39], v[200:201], 1, s[42:43]
	global_store_dwordx4 v[38:39], v[34:37], off
	s_waitcnt lgkmcnt(0)
	v_add_f32_e32 v32, v32, v33
	v_mov_b32_e32 v33, v32
	s_nop 1
	v_permlane32_swap_b32_e32 v33, v32
	s_nop 1
	s_and_saveexec_b64 s[10:11], vcc
	s_cbranch_execz .LBB0_288
	s_waitcnt lgkmcnt(0)
	v_add_f32_e32 v32, v32, v33
	v_mul_f32_e32 v32, 0x49800000, v32
	v_trunc_f32_e32 v32, v32
	v_mul_f32_e32 v33, 0x2f800000, v32
	v_floor_f32_e32 v33, v33
	v_fmac_f32_e32 v32, 0xcf800000, v33
	v_cvt_u32_f32_e32 v32, v32
	v_cvt_u32_f32_e32 v33, v33
	global_atomic_add_x2 v[218:219], v[32:33], off offset:1152
;     __device__ __forceinline__ void operator()(f32x4 (&acc)[2][2][4][2], const Unit& u, int wr, int wc, int fr, int fq) const {
;         const int row0 = u.pm * BM + wr * 64 + fr, col0 = u.pn * BM + wc * 32 + 8 * fq; const unsigned off0 = (unsigned)row0 * 1024u + (unsigned)col0;
;         u32x4 t[4][2];
.LBB0_288:
	s_or_b64 exec, exec, s[10:11]
	s_waitcnt vmcnt(15)
	v_lshlrev_b32_e32 v32, 16, v116
	v_add_f32_e32 v28, v28, v32
	v_and_b32_e32 v32, 0xffff0000, v116
	v_add_f32_e32 v29, v29, v32
	v_lshlrev_b32_e32 v32, 16, v117
	v_add_f32_e32 v30, v30, v32
	v_and_b32_e32 v32, 0xffff0000, v117
	v_add_f32_e32 v31, v31, v32
	v_lshlrev_b32_e32 v32, 16, v118
	v_add_f32_e32 v24, v24, v32
	v_and_b32_e32 v32, 0xffff0000, v118
	v_add_f32_e32 v25, v25, v32
	v_lshlrev_b32_e32 v32, 16, v119
	v_add_f32_e32 v26, v26, v32
	v_and_b32_e32 v32, 0xffff0000, v119
	v_add_f32_e32 v27, v27, v32
	s_waitcnt vmcnt(14)
	v_lshlrev_b32_e32 v32, 16, v120
	v_add_f32_e32 v32, v20, v32
	v_and_b32_e32 v20, 0xffff0000, v120
	s_waitcnt lgkmcnt(0)
	v_add_f32_e32 v33, v21, v20
	v_lshlrev_b32_e32 v20, 16, v121
	v_add_f32_e32 v22, v22, v20
	v_and_b32_e32 v20, 0xffff0000, v121
	v_add_f32_e32 v23, v23, v20
	v_lshlrev_b32_e32 v20, 16, v122
	v_add_f32_e32 v34, v16, v20
	v_and_b32_e32 v16, 0xffff0000, v122
	v_add_f32_e32 v35, v17, v16
	v_lshlrev_b32_e32 v16, 16, v123
	v_add_f32_e32 v36, v18, v16
	v_and_b32_e32 v16, 0xffff0000, v123
	v_add_f32_e32 v37, v19, v16
	v_cvt_pk_bf16_f32 v16, v28, v29
	v_lshl_add_u64 v[20:21], v[198:199], 1, s[42:43]
	v_cvt_pk_bf16_f32 v17, v30, v31
	v_cvt_pk_bf16_f32 v18, v24, v25
	v_cvt_pk_bf16_f32 v19, v26, v27
	global_store_dwordx4 v[20:21], v[16:19], off
	v_lshlrev_b32_e32 v20, 16, v16
	s_nop 0
	v_and_b32_e32 v16, 0xffff0000, v16
	v_mul_f32_e32 v16, v16, v16
	v_fmac_f32_e32 v16, v20, v20
	v_lshlrev_b32_e32 v20, 16, v17
	v_and_b32_e32 v17, 0xffff0000, v17
	v_mul_f32_e32 v17, v17, v17
	v_fmac_f32_e32 v17, v20, v20
	v_add_f32_e32 v16, v16, v17
	v_lshlrev_b32_e32 v17, 16, v18
	v_and_b32_e32 v18, 0xffff0000, v18
	v_mul_f32_e32 v18, v18, v18
	v_fmac_f32_e32 v18, v17, v17
	v_add_f32_e32 v16, v16, v18
	v_and_b32_e32 v18, 0xffff0000, v19
	v_lshlrev_b32_e32 v17, 16, v19
	v_mul_f32_e32 v18, v18, v18
	v_fmac_f32_e32 v18, v17, v17
	v_add_f32_e32 v16, v16, v18
	v_cvt_pk_bf16_f32 v18, v32, v33
	v_cvt_pk_bf16_f32 v19, v22, v23
	v_cvt_pk_bf16_f32 v20, v34, v35
	v_cvt_pk_bf16_f32 v21, v36, v37
	s_nop 0
	v_and_b32_e32 v22, 0xffff0000, v18
	v_lshlrev_b32_e32 v17, 16, v18
	v_mul_f32_e32 v22, v22, v22
	v_fmac_f32_e32 v22, v17, v17
	v_add_f32_e32 v16, v16, v22
	v_and_b32_e32 v22, 0xffff0000, v19
	v_lshlrev_b32_e32 v17, 16, v19
	v_mul_f32_e32 v22, v22, v22
	v_fmac_f32_e32 v22, v17, v17
	v_add_f32_e32 v16, v16, v22
	v_and_b32_e32 v22, 0xffff0000, v20
	v_lshlrev_b32_e32 v17, 16, v20
	v_mul_f32_e32 v22, v22, v22
	v_fmac_f32_e32 v22, v17, v17
	v_add_f32_e32 v16, v16, v22
	v_and_b32_e32 v22, 0xffff0000, v21
	v_lshlrev_b32_e32 v17, 16, v21
	v_mul_f32_e32 v22, v22, v22
	v_fmac_f32_e32 v22, v17, v17
	v_add_f32_e32 v16, v16, v22
	v_mov_b32_e32 v17, v16
	s_nop 1
	v_permlane16_swap_b32_e32 v17, v16
	s_nop 1
	v_lshl_add_u64 v[22:23], v[196:197], 1, s[42:43]
	global_store_dwordx4 v[22:23], v[18:21], off
	s_waitcnt lgkmcnt(0)
	v_add_f32_e32 v16, v16, v17
	v_mov_b32_e32 v17, v16
	s_nop 1
	v_permlane32_swap_b32_e32 v17, v16
	s_nop 1
	s_and_saveexec_b64 s[10:11], vcc
	s_cbranch_execz .LBB0_290
	s_waitcnt lgkmcnt(0)
	v_add_f32_e32 v16, v16, v17
	v_mul_f32_e32 v16, 0x49800000, v16
	v_trunc_f32_e32 v16, v16
	v_mul_f32_e32 v17, 0x2f800000, v16
	v_floor_f32_e32 v17, v17
	v_fmac_f32_e32 v16, 0xcf800000, v17
	v_cvt_u32_f32_e32 v16, v16
	v_cvt_u32_f32_e32 v17, v17
	global_atomic_add_x2 v[218:219], v[16:17], off offset:1280
.LBB0_290:
	s_or_b64 exec, exec, s[10:11]
	s_waitcnt vmcnt(15)
	v_lshlrev_b32_e32 v16, 16, v112
	v_add_f32_e32 v12, v12, v16
	v_and_b32_e32 v16, 0xffff0000, v112
	v_add_f32_e32 v13, v13, v16
	v_lshlrev_b32_e32 v16, 16, v113
	v_add_f32_e32 v14, v14, v16
	v_and_b32_e32 v16, 0xffff0000, v113
	v_add_f32_e32 v15, v15, v16
	v_lshlrev_b32_e32 v16, 16, v114
	v_add_f32_e32 v8, v8, v16
	v_and_b32_e32 v16, 0xffff0000, v114
	v_add_f32_e32 v9, v9, v16
	v_lshlrev_b32_e32 v16, 16, v115
	v_add_f32_e32 v10, v10, v16
	v_and_b32_e32 v16, 0xffff0000, v115
	v_add_f32_e32 v11, v11, v16
	s_waitcnt vmcnt(14)
	v_lshlrev_b32_e32 v16, 16, v140
	v_add_f32_e32 v16, v4, v16
	v_and_b32_e32 v4, 0xffff0000, v140
	s_waitcnt lgkmcnt(0)
	v_add_f32_e32 v17, v5, v4
	v_lshlrev_b32_e32 v4, 16, v141
	v_add_f32_e32 v6, v6, v4
	v_and_b32_e32 v4, 0xffff0000, v141
	v_add_f32_e32 v7, v7, v4
	v_lshlrev_b32_e32 v4, 16, v142
	v_add_f32_e32 v18, v0, v4
	v_and_b32_e32 v0, 0xffff0000, v142
	v_add_f32_e32 v19, v1, v0
	v_lshlrev_b32_e32 v0, 16, v143
	v_add_f32_e32 v20, v2, v0
	v_and_b32_e32 v0, 0xffff0000, v143
	v_add_f32_e32 v21, v3, v0
	v_cvt_pk_bf16_f32 v0, v12, v13
	v_lshl_add_u64 v[4:5], v[194:195], 1, s[42:43]
	v_cvt_pk_bf16_f32 v1, v14, v15
	v_cvt_pk_bf16_f32 v2, v8, v9
	v_cvt_pk_bf16_f32 v3, v10, v11
	global_store_dwordx4 v[4:5], v[0:3], off
	v_lshlrev_b32_e32 v4, 16, v0
	s_nop 0
	v_and_b32_e32 v0, 0xffff0000, v0
	v_mul_f32_e32 v0, v0, v0
	v_fmac_f32_e32 v0, v4, v4
	v_lshlrev_b32_e32 v4, 16, v1
	v_and_b32_e32 v1, 0xffff0000, v1
	v_mul_f32_e32 v1, v1, v1
	v_fmac_f32_e32 v1, v4, v4
	v_add_f32_e32 v0, v0, v1
	v_lshlrev_b32_e32 v1, 16, v2
	v_and_b32_e32 v2, 0xffff0000, v2
	v_mul_f32_e32 v2, v2, v2
	v_fmac_f32_e32 v2, v1, v1
	v_add_f32_e32 v0, v0, v2
	v_and_b32_e32 v2, 0xffff0000, v3
	v_lshlrev_b32_e32 v1, 16, v3
	v_mul_f32_e32 v2, v2, v2
	v_fmac_f32_e32 v2, v1, v1
	v_add_f32_e32 v0, v0, v2
	v_cvt_pk_bf16_f32 v2, v16, v17
	v_cvt_pk_bf16_f32 v3, v6, v7
	v_cvt_pk_bf16_f32 v4, v18, v19
	v_cvt_pk_bf16_f32 v5, v20, v21
	s_nop 0
	v_and_b32_e32 v6, 0xffff0000, v2
	v_lshlrev_b32_e32 v1, 16, v2
	v_mul_f32_e32 v6, v6, v6
	v_fmac_f32_e32 v6, v1, v1
	v_add_f32_e32 v0, v0, v6
	v_and_b32_e32 v6, 0xffff0000, v3
	v_lshlrev_b32_e32 v1, 16, v3
	v_mul_f32_e32 v6, v6, v6
	v_fmac_f32_e32 v6, v1, v1
	v_add_f32_e32 v0, v0, v6
	v_and_b32_e32 v6, 0xffff0000, v4
	v_lshlrev_b32_e32 v1, 16, v4
	v_mul_f32_e32 v6, v6, v6
	v_fmac_f32_e32 v6, v1, v1
	v_add_f32_e32 v0, v0, v6
	v_and_b32_e32 v6, 0xffff0000, v5
	v_lshlrev_b32_e32 v1, 16, v5
	v_mul_f32_e32 v6, v6, v6
	v_fmac_f32_e32 v6, v1, v1
	v_add_f32_e32 v0, v0, v6
	v_mov_b32_e32 v1, v0
	s_nop 1
	v_permlane16_swap_b32_e32 v1, v0
	s_nop 1
	v_lshl_add_u64 v[6:7], v[192:193], 1, s[42:43]
	global_store_dwordx4 v[6:7], v[2:5], off
	s_waitcnt lgkmcnt(0)
	v_add_f32_e32 v0, v0, v1
	v_mov_b32_e32 v1, v0
	s_nop 1
	v_permlane32_swap_b32_e32 v1, v0
	s_nop 1
	s_and_saveexec_b64 s[10:11], vcc
	s_cbranch_execz .LBB0_265
	s_waitcnt lgkmcnt(0)
	v_add_f32_e32 v0, v0, v1
	v_mul_f32_e32 v0, 0x49800000, v0
	v_trunc_f32_e32 v0, v0
	v_mul_f32_e32 v1, 0x2f800000, v0
	v_floor_f32_e32 v1, v1
	v_fmac_f32_e32 v0, 0xcf800000, v1
	v_cvt_u32_f32_e32 v0, v0
	v_cvt_u32_f32_e32 v1, v1
	global_atomic_add_x2 v[218:219], v[0:1], off offset:1408
	s_branch .LBB0_265
